# ssd_out unit: the second token half also issues its 16 y/z loads together
# baseline (speedup 1.0000x reference)
.LBB0_1290:
	s_or_b64 exec, exec, s[4:5]
	v_readlane_b32 s2, v254, 53
	s_waitcnt lgkmcnt(0)
	s_barrier
	v_mov_b32_e32 v0, s2
	ds_read_b32 v0, v0
	s_mov_b64 s[4:5], -1
	s_waitcnt lgkmcnt(0)
	v_readfirstlane_b32 s2, v0
	s_cmpk_gt_i32 s2, 0xff
	s_cbranch_scc1 .LBB0_1285
	s_ashr_i32 s4, s2, 5
	s_and_b32 s3, s2, 31
	s_ashr_i32 s5, s4, 31
	s_lshl_b32 s2, s2, 2
	s_lshl_b32 s16, s3, 6
	s_lshl_b64 s[14:15], s[4:5], 7
	s_and_b32 s2, s2, 0x78
	s_add_u32 s3, s14, s88
	s_addc_u32 s14, s15, 0
	s_add_u32 s2, s3, s2
	s_addc_u32 s3, s14, 0
	s_lshl_b64 s[2:3], s[2:3], 14
	v_lshl_add_u64 v[4:5], v[86:87], 0, s[2:3]
	v_mov_b32_e32 v103, v96
	v_mov_b32_e32 v105, v96
	s_lshl_b64 s[4:5], s[4:5], 11
	v_lshl_add_u64 v[80:81], v[4:5], 0, v[102:103]
	v_lshl_add_u64 v[82:83], v[4:5], 0, v[104:105]
	s_or_b32 s4, s4, s16
	global_load_dwordx4 v[0:3], v[80:81], off
	global_load_dwordx4 v[4:7], v[82:83], off
	s_lshl_b64 s[14:15], s[4:5], 9
	v_lshl_add_u64 v[12:13], v[88:89], 0, s[14:15]
	v_mov_b32_e32 v107, v96
	v_mov_b32_e32 v109, v96
	v_lshl_add_u64 v[110:111], v[12:13], 0, v[106:107]
	v_lshl_add_u64 v[112:113], v[12:13], 0, v[108:109]
	global_load_dwordx4 v[8:11], v[110:111], off
	global_load_dwordx4 v[12:15], v[112:113], off
	global_load_dwordx4 v[64:67], v[80:81], off offset:32
	global_load_dwordx4 v[68:71], v[82:83], off offset:32
	global_load_dwordx4 v[72:75], v[110:111], off offset:32
	global_load_dwordx4 v[76:79], v[112:113], off offset:32
	s_waitcnt vmcnt(5)
	v_mfma_f32_32x32x16_bf16 v[48:63], v[0:3], v[8:11], 0
	v_mfma_f32_32x32x16_bf16 v[32:47], v[4:7], v[8:11], 0
	s_waitcnt vmcnt(4)
	v_mfma_f32_32x32x16_bf16 v[16:31], v[0:3], v[12:15], 0
	v_mfma_f32_32x32x16_bf16 v[0:15], v[4:7], v[12:15], 0
	s_waitcnt vmcnt(1)
	v_mfma_f32_32x32x16_bf16 v[48:63], v[64:67], v[72:75], v[48:63]
	v_mfma_f32_32x32x16_bf16 v[32:47], v[68:71], v[72:75], v[32:47]
	s_waitcnt vmcnt(0)
	v_mfma_f32_32x32x16_bf16 v[16:31], v[64:67], v[76:79], v[16:31]
	v_mfma_f32_32x32x16_bf16 v[0:15], v[68:71], v[76:79], v[0:15]
	global_load_dwordx4 v[64:67], v[80:81], off offset:64
	global_load_dwordx4 v[68:71], v[82:83], off offset:64
	global_load_dwordx4 v[72:75], v[110:111], off offset:64
	global_load_dwordx4 v[76:79], v[112:113], off offset:64
	s_waitcnt vmcnt(1)
	v_mfma_f32_32x32x16_bf16 v[48:63], v[64:67], v[72:75], v[48:63]
	v_mfma_f32_32x32x16_bf16 v[32:47], v[68:71], v[72:75], v[32:47]
	s_waitcnt vmcnt(0)
	v_mfma_f32_32x32x16_bf16 v[16:31], v[64:67], v[76:79], v[16:31]
	v_mfma_f32_32x32x16_bf16 v[0:15], v[68:71], v[76:79], v[0:15]
	global_load_dwordx4 v[64:67], v[80:81], off offset:96
	global_load_dwordx4 v[68:71], v[82:83], off offset:96
	global_load_dwordx4 v[72:75], v[110:111], off offset:96
	global_load_dwordx4 v[76:79], v[112:113], off offset:96
	s_waitcnt vmcnt(1)
	v_mfma_f32_32x32x16_bf16 v[48:63], v[64:67], v[72:75], v[48:63]
	v_mfma_f32_32x32x16_bf16 v[32:47], v[68:71], v[72:75], v[32:47]
	s_waitcnt vmcnt(0)
	v_mfma_f32_32x32x16_bf16 v[16:31], v[64:67], v[76:79], v[16:31]
	v_mfma_f32_32x32x16_bf16 v[0:15], v[68:71], v[76:79], v[0:15]
	global_load_dwordx4 v[64:67], v[80:81], off offset:128
	global_load_dwordx4 v[68:71], v[82:83], off offset:128
	global_load_dwordx4 v[72:75], v[110:111], off offset:128
	global_load_dwordx4 v[76:79], v[112:113], off offset:128
	s_waitcnt vmcnt(1)
	v_mfma_f32_32x32x16_bf16 v[48:63], v[64:67], v[72:75], v[48:63]
	v_mfma_f32_32x32x16_bf16 v[32:47], v[68:71], v[72:75], v[32:47]
	s_waitcnt vmcnt(0)
	v_mfma_f32_32x32x16_bf16 v[16:31], v[64:67], v[76:79], v[16:31]
	v_mfma_f32_32x32x16_bf16 v[0:15], v[68:71], v[76:79], v[0:15]
	global_load_dwordx4 v[64:67], v[80:81], off offset:160
	global_load_dwordx4 v[68:71], v[82:83], off offset:160
	global_load_dwordx4 v[72:75], v[110:111], off offset:160
	global_load_dwordx4 v[76:79], v[112:113], off offset:160
	s_waitcnt vmcnt(1)
	v_mfma_f32_32x32x16_bf16 v[48:63], v[64:67], v[72:75], v[48:63]
	v_mfma_f32_32x32x16_bf16 v[32:47], v[68:71], v[72:75], v[32:47]
	s_waitcnt vmcnt(0)
	v_mfma_f32_32x32x16_bf16 v[16:31], v[64:67], v[76:79], v[16:31]
	v_mfma_f32_32x32x16_bf16 v[0:15], v[68:71], v[76:79], v[0:15]
	global_load_dwordx4 v[64:67], v[80:81], off offset:192
	global_load_dwordx4 v[68:71], v[82:83], off offset:192
	global_load_dwordx4 v[72:75], v[110:111], off offset:192
	global_load_dwordx4 v[76:79], v[112:113], off offset:192
	s_waitcnt vmcnt(1)
	v_mfma_f32_32x32x16_bf16 v[48:63], v[64:67], v[72:75], v[48:63]
	v_mfma_f32_32x32x16_bf16 v[32:47], v[68:71], v[72:75], v[32:47]
	s_waitcnt vmcnt(0)
	v_mfma_f32_32x32x16_bf16 v[16:31], v[64:67], v[76:79], v[16:31]
	v_mfma_f32_32x32x16_bf16 v[0:15], v[68:71], v[76:79], v[0:15]
	global_load_dwordx4 v[64:67], v[80:81], off offset:224
	global_load_dwordx4 v[68:71], v[82:83], off offset:224
	global_load_dwordx4 v[72:75], v[110:111], off offset:224
	global_load_dwordx4 v[76:79], v[112:113], off offset:224
	s_barrier
	s_waitcnt vmcnt(1)
	v_mfma_f32_32x32x16_bf16 v[32:47], v[68:71], v[72:75], v[32:47]
	s_waitcnt vmcnt(0)
	v_mfma_f32_32x32x16_bf16 v[0:15], v[68:71], v[76:79], v[0:15]
	v_mov_b32_e32 v69, s5
	v_or_b32_e32 v68, s4, v84
	v_lshlrev_b64 v[110:111], 11, v[68:69]
	v_mad_u64_u32 v[130:131], s[2:3], v68, s42, v[98:99]
	v_lshl_add_u64 v[128:129], v[94:95], 0, v[110:111]
	v_mfma_f32_32x32x16_bf16 v[48:63], v[64:67], v[72:75], v[48:63]
	v_mfma_f32_32x32x16_bf16 v[16:31], v[64:67], v[76:79], v[16:31]
	v_lshlrev_b64 v[64:65], 5, v[68:69]
	v_lshl_add_u64 v[64:65], s[8:9], 0, v[64:65]
	global_load_dword v142, v[64:65], off
	v_mov_b32_e32 v68, 0x2800
	v_mad_i32_i24 v131, s5, v68, v131
	global_load_dwordx4 v[64:67], v[128:129], off
	global_load_dwordx4 v[112:115], v[130:131], off
	global_load_dwordx4 v[120:123], v[128:129], off offset:32
	global_load_dwordx4 v[132:135], v[130:131], off offset:32
	global_load_dwordx4 v[80:83], v[128:129], off offset:64
	global_load_dwordx4 v[76:79], v[130:131], off offset:64
	global_load_dwordx4 v[72:75], v[128:129], off offset:96
	global_load_dwordx4 v[68:71], v[130:131], off offset:96
	global_load_dwordx4 v[186:189], v[128:129], off offset:128
	global_load_dwordx4 v[190:193], v[130:131], off offset:128
	global_load_dwordx4 v[194:197], v[128:129], off offset:160
	global_load_dwordx4 v[198:201], v[130:131], off offset:160
	global_load_dwordx4 v[202:205], v[128:129], off offset:192
	global_load_dwordx4 v[206:209], v[130:131], off offset:192
	global_load_dwordx4 v[210:213], v[128:129], off offset:224
	global_load_dwordx4 v[214:217], v[130:131], off offset:224
	s_waitcnt vmcnt(16)
	v_exp_f32_e32 v124, v142
	s_waitcnt vmcnt(14)
	v_mul_f32_e32 v103, 0xbfb8aa3b, v112
	v_fma_f32 v105, v112, s43, -v103
	v_rndne_f32_e32 v107, v103
	v_fmac_f32_e32 v105, 0xb2a5705f, v112
	v_sub_f32_e32 v103, v103, v107
	v_add_f32_e32 v103, v103, v105
	v_exp_f32_e32 v103, v103
	v_cvt_i32_f32_e32 v105, v107
	v_cmp_nlt_f32_e32 vcc, s34, v112
	v_pk_fma_f32 v[48:49], v[48:49], v[124:125], v[64:65] op_sel_hi:[1,0,1]
	v_pk_fma_f32 v[50:51], v[50:51], v[124:125], v[66:67] op_sel_hi:[1,0,1]
	v_ldexp_f32 v103, v103, v105
	v_cndmask_b32_e32 v103, 0, v103, vcc
	v_cmp_ngt_f32_e32 vcc, s35, v112
	s_waitcnt vmcnt(13)
	v_pk_fma_f32 v[52:53], v[52:53], v[124:125], v[120:121] op_sel_hi:[1,0,1]
	v_cndmask_b32_e32 v116, v179, v103, vcc
	v_mul_f32_e32 v103, 0xbfb8aa3b, v113
	v_fma_f32 v105, v113, s43, -v103
	v_rndne_f32_e32 v107, v103
	v_fmac_f32_e32 v105, 0xb2a5705f, v113
	v_sub_f32_e32 v103, v103, v107
	v_add_f32_e32 v103, v103, v105
	v_exp_f32_e32 v103, v103
	v_cvt_i32_f32_e32 v105, v107
	v_cmp_nlt_f32_e32 vcc, s34, v113
	v_ldexp_f32 v103, v103, v105
	s_nop 0
	v_cndmask_b32_e32 v103, 0, v103, vcc
	v_cmp_ngt_f32_e32 vcc, s35, v113
	s_nop 1
	v_cndmask_b32_e32 v117, v179, v103, vcc
	v_pk_add_f32 v[64:65], v[116:117], 1.0 op_sel_hi:[1,0]
	s_nop 0
	v_div_scale_f32 v103, s[2:3], v65, v65, v113
	v_rcp_f32_e32 v105, v103
	s_nop 0
	v_fma_f32 v107, -v103, v105, 1.0
	v_fmac_f32_e32 v105, v107, v105
	v_div_scale_f32 v107, vcc, v113, v65, v113
	v_mul_f32_e32 v109, v107, v105
	v_fma_f32 v116, -v103, v109, v107
	v_fmac_f32_e32 v109, v116, v105
	v_fma_f32 v103, -v103, v109, v107
	v_div_fmas_f32 v103, v103, v105, v109
	v_div_fixup_f32 v65, v103, v65, v113
	v_div_scale_f32 v103, s[2:3], v64, v64, v112
	v_rcp_f32_e32 v105, v103
	s_nop 0
	v_fma_f32 v107, -v103, v105, 1.0
	v_fmac_f32_e32 v105, v107, v105
	v_div_scale_f32 v107, vcc, v112, v64, v112
	v_mul_f32_e32 v109, v107, v105
	v_fma_f32 v113, -v103, v109, v107
	v_fmac_f32_e32 v109, v113, v105
	v_fma_f32 v103, -v103, v109, v107
	v_div_fmas_f32 v103, v103, v105, v109
	v_div_fixup_f32 v64, v103, v64, v112
	v_pk_mul_f32 v[116:117], v[48:49], v[64:65]
	v_mul_f32_e32 v64, 0xbfb8aa3b, v114
	v_fma_f32 v65, v114, s43, -v64
	v_rndne_f32_e32 v103, v64
	v_fmac_f32_e32 v65, 0xb2a5705f, v114
	v_sub_f32_e32 v64, v64, v103
	v_add_f32_e32 v64, v64, v65
	v_exp_f32_e32 v64, v64
	v_cvt_i32_f32_e32 v65, v103
	v_cmp_nlt_f32_e32 vcc, s34, v114
	v_mul_f32_e32 v48, v117, v117
	v_pk_fma_f32 v[48:49], v[116:117], v[116:117], v[48:49] op_sel_hi:[1,1,0]
	v_ldexp_f32 v64, v64, v65
	v_mul_f32_e32 v65, 0xbfb8aa3b, v115
	v_fma_f32 v103, v115, s43, -v65
	v_rndne_f32_e32 v105, v65
	v_fmac_f32_e32 v103, 0xb2a5705f, v115
	v_sub_f32_e32 v65, v65, v105
	v_add_f32_e32 v65, v65, v103
	v_exp_f32_e32 v65, v65
	v_cvt_i32_f32_e32 v103, v105
	v_cndmask_b32_e32 v64, 0, v64, vcc
	v_cmp_ngt_f32_e32 vcc, s35, v114
	v_ldexp_f32 v65, v65, v103
	s_nop 0
	v_cndmask_b32_e32 v64, v179, v64, vcc
	v_cmp_nlt_f32_e32 vcc, s34, v115
	s_nop 1
	v_cndmask_b32_e32 v65, 0, v65, vcc
	v_cmp_ngt_f32_e32 vcc, s35, v115
	s_nop 1
	v_cndmask_b32_e32 v65, v179, v65, vcc
	v_pk_add_f32 v[64:65], v[64:65], 1.0 op_sel_hi:[1,0]
	s_nop 0
	v_div_scale_f32 v66, s[2:3], v65, v65, v115
	v_rcp_f32_e32 v67, v66
	s_nop 0
	v_fma_f32 v103, -v66, v67, 1.0
	v_fmac_f32_e32 v67, v103, v67
	v_div_scale_f32 v103, vcc, v115, v65, v115
	v_mul_f32_e32 v105, v103, v67
	v_fma_f32 v107, -v66, v105, v103
	v_fmac_f32_e32 v105, v107, v67
	v_fma_f32 v66, -v66, v105, v103
	v_div_fmas_f32 v66, v66, v67, v105
	v_div_fixup_f32 v65, v66, v65, v115
	v_div_scale_f32 v66, s[2:3], v64, v64, v114
	v_rcp_f32_e32 v67, v66
	s_nop 0
	v_fma_f32 v103, -v66, v67, 1.0
	v_fmac_f32_e32 v67, v103, v67
	v_div_scale_f32 v103, vcc, v114, v64, v114
	v_mul_f32_e32 v105, v103, v67
	v_fma_f32 v107, -v66, v105, v103
	v_fmac_f32_e32 v105, v107, v67
	v_fma_f32 v66, -v66, v105, v103
	v_div_fmas_f32 v66, v66, v67, v105
	v_div_fixup_f32 v64, v66, v64, v114
	v_pk_mul_f32 v[118:119], v[50:51], v[64:65]
	s_waitcnt vmcnt(12)
	v_cmp_nlt_f32_e32 vcc, s34, v132
	v_pk_fma_f32 v[48:49], v[118:119], v[118:119], v[48:49]
	v_mul_f32_e32 v50, v119, v119
	v_pk_add_f32 v[48:49], v[50:51], v[48:49] op_sel_hi:[0,1]
	v_mul_f32_e32 v50, 0xbfb8aa3b, v132
	v_fma_f32 v51, v132, s43, -v50
	v_rndne_f32_e32 v64, v50
	v_fmac_f32_e32 v51, 0xb2a5705f, v132
	v_sub_f32_e32 v50, v50, v64
	v_add_f32_e32 v50, v50, v51
	v_exp_f32_e32 v50, v50
	v_cvt_i32_f32_e32 v51, v64
	v_ldexp_f32 v50, v50, v51
	v_mul_f32_e32 v51, 0xbfb8aa3b, v133
	v_fma_f32 v64, v133, s43, -v51
	v_rndne_f32_e32 v65, v51
	v_fmac_f32_e32 v64, 0xb2a5705f, v133
	v_sub_f32_e32 v51, v51, v65
	v_add_f32_e32 v51, v51, v64
	v_exp_f32_e32 v51, v51
	v_cvt_i32_f32_e32 v64, v65
	v_cndmask_b32_e32 v50, 0, v50, vcc
	v_cmp_ngt_f32_e32 vcc, s35, v132
	v_ldexp_f32 v51, v51, v64
	s_nop 0
	v_cndmask_b32_e32 v50, v179, v50, vcc
	v_cmp_nlt_f32_e32 vcc, s34, v133
	s_nop 1
	v_cndmask_b32_e32 v51, 0, v51, vcc
	v_cmp_ngt_f32_e32 vcc, s35, v133
	s_nop 1
	v_cndmask_b32_e32 v51, v179, v51, vcc
	v_pk_add_f32 v[50:51], v[50:51], 1.0 op_sel_hi:[1,0]
	s_nop 0
	v_div_scale_f32 v64, s[2:3], v51, v51, v133
	v_rcp_f32_e32 v65, v64
	s_nop 0
	v_fma_f32 v66, -v64, v65, 1.0
	v_fmac_f32_e32 v65, v66, v65
	v_div_scale_f32 v66, vcc, v133, v51, v133
	v_mul_f32_e32 v67, v66, v65
	v_fma_f32 v103, -v64, v67, v66
	v_fmac_f32_e32 v67, v103, v65
	v_fma_f32 v64, -v64, v67, v66
	v_div_fmas_f32 v64, v64, v65, v67
	v_div_fixup_f32 v51, v64, v51, v133
	v_div_scale_f32 v64, s[2:3], v50, v50, v132
	v_rcp_f32_e32 v65, v64
	s_nop 0
	v_fma_f32 v66, -v64, v65, 1.0
	v_fmac_f32_e32 v65, v66, v65
	v_div_scale_f32 v66, vcc, v132, v50, v132
	v_mul_f32_e32 v67, v66, v65
	v_fma_f32 v103, -v64, v67, v66
	v_fmac_f32_e32 v67, v103, v65
	v_fma_f32 v64, -v64, v67, v66
	v_div_fmas_f32 v64, v64, v65, v67
	v_div_fixup_f32 v50, v64, v50, v132
	v_pk_mul_f32 v[112:113], v[52:53], v[50:51]
	v_cmp_nlt_f32_e32 vcc, s34, v134
	v_pk_fma_f32 v[48:49], v[112:113], v[112:113], v[48:49]
	v_mul_f32_e32 v50, v113, v113
	v_pk_add_f32 v[48:49], v[50:51], v[48:49] op_sel_hi:[0,1]
	v_mul_f32_e32 v50, 0xbfb8aa3b, v134
	v_fma_f32 v51, v134, s43, -v50
	v_rndne_f32_e32 v52, v50
	v_fmac_f32_e32 v51, 0xb2a5705f, v134
	v_sub_f32_e32 v50, v50, v52
	v_add_f32_e32 v50, v50, v51
	v_exp_f32_e32 v50, v50
	v_cvt_i32_f32_e32 v51, v52
	v_ldexp_f32 v50, v50, v51
	v_mul_f32_e32 v51, 0xbfb8aa3b, v135
	v_fma_f32 v52, v135, s43, -v51
	v_rndne_f32_e32 v53, v51
	v_fmac_f32_e32 v52, 0xb2a5705f, v135
	v_sub_f32_e32 v51, v51, v53
	v_add_f32_e32 v51, v51, v52
	v_exp_f32_e32 v51, v51
	v_cvt_i32_f32_e32 v52, v53
	v_cndmask_b32_e32 v50, 0, v50, vcc
	v_cmp_ngt_f32_e32 vcc, s35, v134
	v_ldexp_f32 v51, v51, v52
	s_nop 0
	v_cndmask_b32_e32 v50, v179, v50, vcc
	v_cmp_nlt_f32_e32 vcc, s34, v135
	v_pk_fma_f32 v[52:53], v[54:55], v[124:125], v[122:123] op_sel_hi:[1,0,1]
	s_nop 0
	v_cndmask_b32_e32 v51, 0, v51, vcc
	v_cmp_ngt_f32_e32 vcc, s35, v135
	s_nop 1
	v_cndmask_b32_e32 v51, v179, v51, vcc
	v_pk_add_f32 v[50:51], v[50:51], 1.0 op_sel_hi:[1,0]
	s_nop 0
	v_div_scale_f32 v54, s[2:3], v51, v51, v135
	v_rcp_f32_e32 v55, v54
	s_nop 0
	v_fma_f32 v64, -v54, v55, 1.0
	v_fmac_f32_e32 v55, v64, v55
	v_div_scale_f32 v64, vcc, v135, v51, v135
	v_mul_f32_e32 v65, v64, v55
	v_fma_f32 v66, -v54, v65, v64
	v_fmac_f32_e32 v65, v66, v55
	v_fma_f32 v54, -v54, v65, v64
	v_div_fmas_f32 v54, v54, v55, v65
	v_div_fixup_f32 v51, v54, v51, v135
	v_div_scale_f32 v54, s[2:3], v50, v50, v134
	v_rcp_f32_e32 v55, v54
	s_nop 0
	v_fma_f32 v64, -v54, v55, 1.0
	v_fmac_f32_e32 v55, v64, v55
	v_div_scale_f32 v64, vcc, v134, v50, v134
	v_mul_f32_e32 v65, v64, v55
	v_fma_f32 v66, -v54, v65, v64
	v_fmac_f32_e32 v65, v66, v55
	v_fma_f32 v54, -v54, v65, v64
	v_div_fmas_f32 v54, v54, v55, v65
	v_div_fixup_f32 v50, v54, v50, v134
	v_pk_mul_f32 v[114:115], v[52:53], v[50:51]
	s_waitcnt vmcnt(10)
	v_cmp_nlt_f32_e32 vcc, s34, v76
	v_pk_fma_f32 v[48:49], v[114:115], v[114:115], v[48:49]
	v_mul_f32_e32 v50, v115, v115
	v_pk_add_f32 v[48:49], v[50:51], v[48:49] op_sel_hi:[0,1]
	v_mul_f32_e32 v50, 0xbfb8aa3b, v76
	v_fma_f32 v51, v76, s43, -v50
	v_rndne_f32_e32 v52, v50
	v_fmac_f32_e32 v51, 0xb2a5705f, v76
	v_sub_f32_e32 v50, v50, v52
	v_add_f32_e32 v50, v50, v51
	v_exp_f32_e32 v50, v50
	v_cvt_i32_f32_e32 v51, v52
	v_ldexp_f32 v50, v50, v51
	v_mul_f32_e32 v51, 0xbfb8aa3b, v77
	v_fma_f32 v52, v77, s43, -v51
	v_rndne_f32_e32 v53, v51
	v_fmac_f32_e32 v52, 0xb2a5705f, v77
	v_sub_f32_e32 v51, v51, v53
	v_add_f32_e32 v51, v51, v52
	v_exp_f32_e32 v51, v51
	v_cvt_i32_f32_e32 v52, v53
	v_cndmask_b32_e32 v50, 0, v50, vcc
	v_cmp_ngt_f32_e32 vcc, s35, v76
	v_ldexp_f32 v51, v51, v52
	s_nop 0
	v_cndmask_b32_e32 v50, v179, v50, vcc
	v_cmp_nlt_f32_e32 vcc, s34, v77
	v_pk_fma_f32 v[52:53], v[56:57], v[124:125], v[80:81] op_sel_hi:[1,0,1]
	s_nop 0
	v_cndmask_b32_e32 v51, 0, v51, vcc
	v_cmp_ngt_f32_e32 vcc, s35, v77
	s_nop 1
	v_cndmask_b32_e32 v51, v179, v51, vcc
	v_pk_add_f32 v[50:51], v[50:51], 1.0 op_sel_hi:[1,0]
	s_nop 0
	v_div_scale_f32 v54, s[2:3], v51, v51, v77
	v_rcp_f32_e32 v55, v54
	s_nop 0
	v_fma_f32 v56, -v54, v55, 1.0
	v_fmac_f32_e32 v55, v56, v55
	v_div_scale_f32 v56, vcc, v77, v51, v77
	v_mul_f32_e32 v57, v56, v55
	v_fma_f32 v64, -v54, v57, v56
	v_fmac_f32_e32 v57, v64, v55
	v_fma_f32 v54, -v54, v57, v56
	v_div_fmas_f32 v54, v54, v55, v57
	v_div_fixup_f32 v51, v54, v51, v77
	v_div_scale_f32 v54, s[2:3], v50, v50, v76
	v_rcp_f32_e32 v55, v54
	s_nop 0
	v_fma_f32 v56, -v54, v55, 1.0
	v_fmac_f32_e32 v55, v56, v55
	v_div_scale_f32 v56, vcc, v76, v50, v76
	v_mul_f32_e32 v57, v56, v55
	v_fma_f32 v64, -v54, v57, v56
	v_fmac_f32_e32 v57, v64, v55
	v_fma_f32 v54, -v54, v57, v56
	v_div_fmas_f32 v54, v54, v55, v57
	v_div_fixup_f32 v50, v54, v50, v76
	v_pk_mul_f32 v[80:81], v[52:53], v[50:51]
	v_cmp_nlt_f32_e32 vcc, s34, v78
	v_pk_fma_f32 v[48:49], v[80:81], v[80:81], v[48:49]
	v_mul_f32_e32 v50, v81, v81
	v_pk_add_f32 v[48:49], v[50:51], v[48:49] op_sel_hi:[0,1]
	v_mul_f32_e32 v50, 0xbfb8aa3b, v78
	v_fma_f32 v51, v78, s43, -v50
	v_rndne_f32_e32 v52, v50
	v_fmac_f32_e32 v51, 0xb2a5705f, v78
	v_sub_f32_e32 v50, v50, v52
	v_add_f32_e32 v50, v50, v51
	v_exp_f32_e32 v50, v50
	v_cvt_i32_f32_e32 v51, v52
	v_ldexp_f32 v50, v50, v51
	v_mul_f32_e32 v51, 0xbfb8aa3b, v79
	v_fma_f32 v52, v79, s43, -v51
	v_rndne_f32_e32 v53, v51
	v_fmac_f32_e32 v52, 0xb2a5705f, v79
	v_sub_f32_e32 v51, v51, v53
	v_add_f32_e32 v51, v51, v52
	v_exp_f32_e32 v51, v51
	v_cvt_i32_f32_e32 v52, v53
	v_cndmask_b32_e32 v50, 0, v50, vcc
	v_cmp_ngt_f32_e32 vcc, s35, v78
	v_ldexp_f32 v51, v51, v52
	s_nop 0
	v_cndmask_b32_e32 v50, v179, v50, vcc
	v_cmp_nlt_f32_e32 vcc, s34, v79
	v_pk_fma_f32 v[52:53], v[58:59], v[124:125], v[82:83] op_sel_hi:[1,0,1]
	s_nop 0
	v_cndmask_b32_e32 v51, 0, v51, vcc
	v_cmp_ngt_f32_e32 vcc, s35, v79
	s_nop 1
	v_cndmask_b32_e32 v51, v179, v51, vcc
	v_pk_add_f32 v[50:51], v[50:51], 1.0 op_sel_hi:[1,0]
	s_nop 0
	v_div_scale_f32 v54, s[2:3], v51, v51, v79
	v_rcp_f32_e32 v55, v54
	s_nop 0
	v_fma_f32 v56, -v54, v55, 1.0
	v_fmac_f32_e32 v55, v56, v55
	v_div_scale_f32 v56, vcc, v79, v51, v79
	v_mul_f32_e32 v57, v56, v55
	v_fma_f32 v58, -v54, v57, v56
	v_fmac_f32_e32 v57, v58, v55
	v_fma_f32 v54, -v54, v57, v56
	v_div_fmas_f32 v54, v54, v55, v57
	v_div_fixup_f32 v51, v54, v51, v79
	v_div_scale_f32 v54, s[2:3], v50, v50, v78
	v_rcp_f32_e32 v55, v54
	s_nop 0
	v_fma_f32 v56, -v54, v55, 1.0
	v_fmac_f32_e32 v55, v56, v55
	v_div_scale_f32 v56, vcc, v78, v50, v78
	v_mul_f32_e32 v57, v56, v55
	v_fma_f32 v58, -v54, v57, v56
	v_fmac_f32_e32 v57, v58, v55
	v_fma_f32 v54, -v54, v57, v56
	v_div_fmas_f32 v54, v54, v55, v57
	v_div_fixup_f32 v50, v54, v50, v78
	v_pk_mul_f32 v[82:83], v[52:53], v[50:51]
	s_waitcnt vmcnt(8)
	v_cmp_nlt_f32_e32 vcc, s34, v68
	v_pk_fma_f32 v[48:49], v[82:83], v[82:83], v[48:49]
	v_mul_f32_e32 v50, v83, v83
	v_pk_add_f32 v[48:49], v[50:51], v[48:49] op_sel_hi:[0,1]
	v_mul_f32_e32 v50, 0xbfb8aa3b, v68
	v_fma_f32 v51, v68, s43, -v50
	v_rndne_f32_e32 v52, v50
	v_fmac_f32_e32 v51, 0xb2a5705f, v68
	v_sub_f32_e32 v50, v50, v52
	v_add_f32_e32 v50, v50, v51
	v_exp_f32_e32 v50, v50
	v_cvt_i32_f32_e32 v51, v52
	v_ldexp_f32 v50, v50, v51
	v_mul_f32_e32 v51, 0xbfb8aa3b, v69
	v_fma_f32 v52, v69, s43, -v51
	v_rndne_f32_e32 v53, v51
	v_fmac_f32_e32 v52, 0xb2a5705f, v69
	v_sub_f32_e32 v51, v51, v53
	v_add_f32_e32 v51, v51, v52
	v_exp_f32_e32 v51, v51
	v_cvt_i32_f32_e32 v52, v53
	v_cndmask_b32_e32 v50, 0, v50, vcc
	v_cmp_ngt_f32_e32 vcc, s35, v68
	v_ldexp_f32 v51, v51, v52
	s_nop 0
	v_cndmask_b32_e32 v50, v179, v50, vcc
	v_cmp_nlt_f32_e32 vcc, s34, v69
	v_pk_fma_f32 v[52:53], v[60:61], v[124:125], v[72:73] op_sel_hi:[1,0,1]
	s_nop 0
	v_cndmask_b32_e32 v51, 0, v51, vcc
	v_cmp_ngt_f32_e32 vcc, s35, v69
	s_nop 1
	v_cndmask_b32_e32 v51, v179, v51, vcc
	v_pk_add_f32 v[50:51], v[50:51], 1.0 op_sel_hi:[1,0]
	s_nop 0
	v_div_scale_f32 v54, s[2:3], v51, v51, v69
	v_rcp_f32_e32 v55, v54
	s_nop 0
	v_fma_f32 v56, -v54, v55, 1.0
	v_fmac_f32_e32 v55, v56, v55
	v_div_scale_f32 v56, vcc, v69, v51, v69
	v_mul_f32_e32 v57, v56, v55
	v_fma_f32 v58, -v54, v57, v56
	v_fmac_f32_e32 v57, v58, v55
	v_fma_f32 v54, -v54, v57, v56
	v_div_fmas_f32 v54, v54, v55, v57
	v_div_fixup_f32 v51, v54, v51, v69
	v_div_scale_f32 v54, s[2:3], v50, v50, v68
	v_rcp_f32_e32 v55, v54
	s_nop 0
	v_fma_f32 v56, -v54, v55, 1.0
	v_fmac_f32_e32 v55, v56, v55
	v_div_scale_f32 v56, vcc, v68, v50, v68
	v_mul_f32_e32 v57, v56, v55
	v_fma_f32 v58, -v54, v57, v56
	v_fmac_f32_e32 v57, v58, v55
	v_fma_f32 v54, -v54, v57, v56
	v_div_fmas_f32 v54, v54, v55, v57
	v_div_fixup_f32 v50, v54, v50, v68
	v_pk_mul_f32 v[120:121], v[52:53], v[50:51]
	v_cmp_nlt_f32_e32 vcc, s34, v70
	v_pk_fma_f32 v[48:49], v[120:121], v[120:121], v[48:49]
	v_mul_f32_e32 v50, v121, v121
	v_pk_add_f32 v[48:49], v[50:51], v[48:49] op_sel_hi:[0,1]
	v_mul_f32_e32 v50, 0xbfb8aa3b, v70
	v_fma_f32 v51, v70, s43, -v50
	v_rndne_f32_e32 v52, v50
	v_fmac_f32_e32 v51, 0xb2a5705f, v70
	v_sub_f32_e32 v50, v50, v52
	v_add_f32_e32 v50, v50, v51
	v_exp_f32_e32 v50, v50
	v_cvt_i32_f32_e32 v51, v52
	v_ldexp_f32 v50, v50, v51
	v_mul_f32_e32 v51, 0xbfb8aa3b, v71
	v_fma_f32 v52, v71, s43, -v51
	v_rndne_f32_e32 v53, v51
	v_fmac_f32_e32 v52, 0xb2a5705f, v71
	v_sub_f32_e32 v51, v51, v53
	v_add_f32_e32 v51, v51, v52
	v_exp_f32_e32 v51, v51
	v_cvt_i32_f32_e32 v52, v53
	v_cndmask_b32_e32 v50, 0, v50, vcc
	v_cmp_ngt_f32_e32 vcc, s35, v70
	v_ldexp_f32 v51, v51, v52
	s_nop 0
	v_cndmask_b32_e32 v50, v179, v50, vcc
	v_cmp_nlt_f32_e32 vcc, s34, v71
	v_pk_fma_f32 v[52:53], v[62:63], v[124:125], v[74:75] op_sel_hi:[1,0,1]
	s_nop 0
	v_cndmask_b32_e32 v51, 0, v51, vcc
	v_cmp_ngt_f32_e32 vcc, s35, v71
	s_nop 1
	v_cndmask_b32_e32 v51, v179, v51, vcc
	v_pk_add_f32 v[50:51], v[50:51], 1.0 op_sel_hi:[1,0]
	s_nop 0
	v_div_scale_f32 v54, s[2:3], v51, v51, v71
	v_rcp_f32_e32 v55, v54
	s_nop 0
	v_fma_f32 v56, -v54, v55, 1.0
	v_fmac_f32_e32 v55, v56, v55
	v_div_scale_f32 v56, vcc, v71, v51, v71
	v_mul_f32_e32 v57, v56, v55
	v_fma_f32 v58, -v54, v57, v56
	v_fmac_f32_e32 v57, v58, v55
	v_fma_f32 v54, -v54, v57, v56
	v_div_fmas_f32 v54, v54, v55, v57
	v_div_fixup_f32 v51, v54, v51, v71
	v_div_scale_f32 v54, s[2:3], v50, v50, v70
	v_rcp_f32_e32 v55, v54
	s_nop 0
	v_fma_f32 v56, -v54, v55, 1.0
	v_fmac_f32_e32 v55, v56, v55
	v_div_scale_f32 v56, vcc, v70, v50, v70
	v_mul_f32_e32 v57, v56, v55
	v_fma_f32 v58, -v54, v57, v56
	v_fmac_f32_e32 v57, v58, v55
	v_fma_f32 v54, -v54, v57, v56
	v_div_fmas_f32 v54, v54, v55, v57
	v_div_fixup_f32 v50, v54, v50, v70
	v_pk_mul_f32 v[122:123], v[52:53], v[50:51]
	s_nop 0
	v_pk_fma_f32 v[48:49], v[122:123], v[122:123], v[48:49]
	v_mul_f32_e32 v50, v123, v123
	v_pk_add_f32 v[126:127], v[50:51], v[48:49] op_sel_hi:[0,1]
	s_waitcnt vmcnt(7)
	v_pk_fma_f32 v[32:33], v[32:33], v[124:125], v[186:187] op_sel_hi:[1,0,1]
	s_waitcnt vmcnt(6)
	v_mul_f32_e32 v103, 0xbfb8aa3b, v190
	v_fma_f32 v105, v190, s43, -v103
	v_rndne_f32_e32 v107, v103
	v_fmac_f32_e32 v105, 0xb2a5705f, v190
	v_sub_f32_e32 v103, v103, v107
	v_add_f32_e32 v103, v103, v105
	v_exp_f32_e32 v103, v103
	v_cvt_i32_f32_e32 v105, v107
	v_cmp_nlt_f32_e32 vcc, s34, v190
	v_ldexp_f32 v103, v103, v105
	s_nop 0
	v_cndmask_b32_e32 v103, 0, v103, vcc
	v_cmp_ngt_f32_e32 vcc, s35, v190
	s_nop 1
	v_cndmask_b32_e32 v128, v179, v103, vcc
	v_mul_f32_e32 v103, 0xbfb8aa3b, v191
	v_fma_f32 v105, v191, s43, -v103
	v_rndne_f32_e32 v107, v103
	v_fmac_f32_e32 v105, 0xb2a5705f, v191
	v_sub_f32_e32 v103, v103, v107
	v_add_f32_e32 v103, v103, v105
	v_exp_f32_e32 v103, v103
	v_cvt_i32_f32_e32 v105, v107
	v_cmp_nlt_f32_e32 vcc, s34, v191
	v_ldexp_f32 v103, v103, v105
	s_nop 0
	v_cndmask_b32_e32 v103, 0, v103, vcc
	v_cmp_ngt_f32_e32 vcc, s35, v191
	s_nop 1
	v_cndmask_b32_e32 v129, v179, v103, vcc
	v_pk_add_f32 v[68:69], v[128:129], 1.0 op_sel_hi:[1,0]
	s_nop 0
	v_div_scale_f32 v103, s[2:3], v69, v69, v191
	v_rcp_f32_e32 v105, v103
	s_nop 0
	v_fma_f32 v107, -v103, v105, 1.0
	v_fmac_f32_e32 v105, v107, v105
	v_div_scale_f32 v107, vcc, v191, v69, v191
	v_mul_f32_e32 v109, v107, v105
	v_fma_f32 v125, -v103, v109, v107
	v_fmac_f32_e32 v109, v125, v105
	v_fma_f32 v103, -v103, v109, v107
	v_div_fmas_f32 v103, v103, v105, v109
	v_div_fixup_f32 v65, v103, v69, v191
	v_div_scale_f32 v69, s[2:3], v68, v68, v190
	v_rcp_f32_e32 v103, v69
	v_pk_fma_f32 v[34:35], v[34:35], v[124:125], v[188:189] op_sel_hi:[1,0,1]
	s_waitcnt vmcnt(5)
	v_pk_fma_f32 v[36:37], v[36:37], v[124:125], v[194:195] op_sel_hi:[1,0,1]
	v_fma_f32 v105, -v69, v103, 1.0
	v_fmac_f32_e32 v103, v105, v103
	v_div_scale_f32 v105, vcc, v190, v68, v190
	v_mul_f32_e32 v107, v105, v103
	v_fma_f32 v109, -v69, v107, v105
	v_fmac_f32_e32 v107, v109, v103
	v_fma_f32 v69, -v69, v107, v105
	v_div_fmas_f32 v69, v69, v103, v107
	v_div_fixup_f32 v64, v69, v68, v190
	v_pk_mul_f32 v[64:65], v[32:33], v[64:65]
	v_cmp_nlt_f32_e32 vcc, s34, v192
	v_pk_fma_f32 v[32:33], v[64:65], v[64:65], v[126:127]
	v_mul_f32_e32 v68, v65, v65
	v_pk_add_f32 v[32:33], v[68:69], v[32:33] op_sel_hi:[0,1]
	v_mul_f32_e32 v68, 0xbfb8aa3b, v192
	v_fma_f32 v69, v192, s43, -v68
	v_rndne_f32_e32 v103, v68
	v_fmac_f32_e32 v69, 0xb2a5705f, v192
	v_sub_f32_e32 v68, v68, v103
	v_add_f32_e32 v68, v68, v69
	v_exp_f32_e32 v68, v68
	v_cvt_i32_f32_e32 v69, v103
	v_ldexp_f32 v68, v68, v69
	v_mul_f32_e32 v69, 0xbfb8aa3b, v193
	v_fma_f32 v103, v193, s43, -v69
	v_rndne_f32_e32 v105, v69
	v_fmac_f32_e32 v103, 0xb2a5705f, v193
	v_sub_f32_e32 v69, v69, v105
	v_add_f32_e32 v69, v69, v103
	v_exp_f32_e32 v69, v69
	v_cvt_i32_f32_e32 v103, v105
	v_cndmask_b32_e32 v68, 0, v68, vcc
	v_cmp_ngt_f32_e32 vcc, s35, v192
	v_ldexp_f32 v69, v69, v103
	s_nop 0
	v_cndmask_b32_e32 v68, v179, v68, vcc
	v_cmp_nlt_f32_e32 vcc, s34, v193
	s_nop 1
	v_cndmask_b32_e32 v69, 0, v69, vcc
	v_cmp_ngt_f32_e32 vcc, s35, v193
	s_nop 1
	v_cndmask_b32_e32 v69, v179, v69, vcc
	v_pk_add_f32 v[68:69], v[68:69], 1.0 op_sel_hi:[1,0]
	s_nop 0
	v_div_scale_f32 v70, s[2:3], v69, v69, v193
	v_rcp_f32_e32 v71, v70
	s_nop 0
	v_fma_f32 v103, -v70, v71, 1.0
	v_fmac_f32_e32 v71, v103, v71
	v_div_scale_f32 v103, vcc, v193, v69, v193
	v_mul_f32_e32 v105, v103, v71
	v_fma_f32 v107, -v70, v105, v103
	v_fmac_f32_e32 v105, v107, v71
	v_fma_f32 v70, -v70, v105, v103
	v_div_fmas_f32 v70, v70, v71, v105
	v_div_fixup_f32 v67, v70, v69, v193
	v_div_scale_f32 v69, s[2:3], v68, v68, v192
	v_rcp_f32_e32 v70, v69
	s_nop 0
	v_fma_f32 v71, -v69, v70, 1.0
	v_fmac_f32_e32 v70, v71, v70
	v_div_scale_f32 v71, vcc, v192, v68, v192
	v_mul_f32_e32 v103, v71, v70
	v_fma_f32 v105, -v69, v103, v71
	v_fmac_f32_e32 v103, v105, v70
	v_fma_f32 v69, -v69, v103, v71
	v_div_fmas_f32 v69, v69, v70, v103
	v_div_fixup_f32 v66, v69, v68, v192
	v_pk_mul_f32 v[66:67], v[34:35], v[66:67]
	s_waitcnt vmcnt(4)
	v_cmp_nlt_f32_e32 vcc, s34, v198
	v_pk_fma_f32 v[32:33], v[66:67], v[66:67], v[32:33]
	v_mul_f32_e32 v34, v67, v67
	v_pk_add_f32 v[32:33], v[34:35], v[32:33] op_sel_hi:[0,1]
	v_mul_f32_e32 v34, 0xbfb8aa3b, v198
	v_fma_f32 v35, v198, s43, -v34
	v_rndne_f32_e32 v68, v34
	v_fmac_f32_e32 v35, 0xb2a5705f, v198
	v_sub_f32_e32 v34, v34, v68
	v_add_f32_e32 v34, v34, v35
	v_exp_f32_e32 v34, v34
	v_cvt_i32_f32_e32 v35, v68
	v_ldexp_f32 v34, v34, v35
	v_mul_f32_e32 v35, 0xbfb8aa3b, v199
	v_fma_f32 v68, v199, s43, -v35
	v_rndne_f32_e32 v69, v35
	v_fmac_f32_e32 v68, 0xb2a5705f, v199
	v_sub_f32_e32 v35, v35, v69
	v_add_f32_e32 v35, v35, v68
	v_exp_f32_e32 v35, v35
	v_cvt_i32_f32_e32 v68, v69
	v_cndmask_b32_e32 v34, 0, v34, vcc
	v_cmp_ngt_f32_e32 vcc, s35, v198
	v_ldexp_f32 v35, v35, v68
	s_nop 0
	v_cndmask_b32_e32 v34, v179, v34, vcc
	v_cmp_nlt_f32_e32 vcc, s34, v199
	s_nop 1
	v_cndmask_b32_e32 v35, 0, v35, vcc
	v_cmp_ngt_f32_e32 vcc, s35, v199
	s_nop 1
	v_cndmask_b32_e32 v35, v179, v35, vcc
	v_pk_add_f32 v[34:35], v[34:35], 1.0 op_sel_hi:[1,0]
	s_nop 0
	v_div_scale_f32 v60, s[2:3], v35, v35, v199
	v_rcp_f32_e32 v61, v60
	s_nop 0
	v_fma_f32 v68, -v60, v61, 1.0
	v_fmac_f32_e32 v61, v68, v61
	v_div_scale_f32 v68, vcc, v199, v35, v199
	v_mul_f32_e32 v69, v68, v61
	v_fma_f32 v70, -v60, v69, v68
	v_fmac_f32_e32 v69, v70, v61
	v_fma_f32 v60, -v60, v69, v68
	v_div_fmas_f32 v60, v60, v61, v69
	v_div_fixup_f32 v35, v60, v35, v199
	v_div_scale_f32 v57, s[2:3], v34, v34, v198
	v_rcp_f32_e32 v60, v57
	s_nop 0
	v_fma_f32 v61, -v57, v60, 1.0
	v_fmac_f32_e32 v60, v61, v60
	v_div_scale_f32 v61, vcc, v198, v34, v198
	v_mul_f32_e32 v68, v61, v60
	v_fma_f32 v69, -v57, v68, v61
	v_fmac_f32_e32 v68, v69, v60
	v_fma_f32 v57, -v57, v68, v61
	v_div_fmas_f32 v57, v57, v60, v68
	v_div_fixup_f32 v34, v57, v34, v198
	v_pk_mul_f32 v[56:57], v[36:37], v[34:35]
	v_cmp_nlt_f32_e32 vcc, s34, v200
	v_pk_fma_f32 v[32:33], v[56:57], v[56:57], v[32:33]
	v_mul_f32_e32 v34, v57, v57
	v_pk_add_f32 v[32:33], v[34:35], v[32:33] op_sel_hi:[0,1]
	v_mul_f32_e32 v34, 0xbfb8aa3b, v200
	v_fma_f32 v35, v200, s43, -v34
	v_rndne_f32_e32 v36, v34
	v_fmac_f32_e32 v35, 0xb2a5705f, v200
	v_sub_f32_e32 v34, v34, v36
	v_add_f32_e32 v34, v34, v35
	v_exp_f32_e32 v34, v34
	v_cvt_i32_f32_e32 v35, v36
	v_ldexp_f32 v34, v34, v35
	v_mul_f32_e32 v35, 0xbfb8aa3b, v201
	v_fma_f32 v36, v201, s43, -v35
	v_rndne_f32_e32 v37, v35
	v_fmac_f32_e32 v36, 0xb2a5705f, v201
	v_sub_f32_e32 v35, v35, v37
	v_add_f32_e32 v35, v35, v36
	v_exp_f32_e32 v35, v35
	v_cvt_i32_f32_e32 v36, v37
	v_cndmask_b32_e32 v34, 0, v34, vcc
	v_cmp_ngt_f32_e32 vcc, s35, v200
	v_ldexp_f32 v35, v35, v36
	s_nop 0
	v_cndmask_b32_e32 v34, v179, v34, vcc
	v_cmp_nlt_f32_e32 vcc, s34, v201
	v_pk_fma_f32 v[36:37], v[38:39], v[124:125], v[196:197] op_sel_hi:[1,0,1]
	s_nop 0
	v_cndmask_b32_e32 v35, 0, v35, vcc
	v_cmp_ngt_f32_e32 vcc, s35, v201
	s_nop 1
	v_cndmask_b32_e32 v35, v179, v35, vcc
	v_pk_add_f32 v[34:35], v[34:35], 1.0 op_sel_hi:[1,0]
	s_nop 0
	v_div_scale_f32 v38, s[2:3], v35, v35, v201
	v_rcp_f32_e32 v39, v38
	s_nop 0
	v_fma_f32 v60, -v38, v39, 1.0
	v_fmac_f32_e32 v39, v60, v39
	v_div_scale_f32 v60, vcc, v201, v35, v201
	v_mul_f32_e32 v61, v60, v39
	v_fma_f32 v62, -v38, v61, v60
	v_fmac_f32_e32 v61, v62, v39
	v_fma_f32 v38, -v38, v61, v60
	v_div_fmas_f32 v38, v38, v39, v61
	v_div_fixup_f32 v35, v38, v35, v201
	v_div_scale_f32 v38, s[2:3], v34, v34, v200
	v_rcp_f32_e32 v39, v38
	s_nop 0
	v_fma_f32 v59, -v38, v39, 1.0
	v_fmac_f32_e32 v39, v59, v39
	v_div_scale_f32 v59, vcc, v200, v34, v200
	v_mul_f32_e32 v60, v59, v39
	v_fma_f32 v61, -v38, v60, v59
	v_fmac_f32_e32 v60, v61, v39
	v_fma_f32 v38, -v38, v60, v59
	v_div_fmas_f32 v38, v38, v39, v60
	v_div_fixup_f32 v34, v38, v34, v200
	v_pk_mul_f32 v[58:59], v[36:37], v[34:35]
	s_waitcnt vmcnt(2)
	v_cmp_nlt_f32_e32 vcc, s34, v206
	v_pk_fma_f32 v[32:33], v[58:59], v[58:59], v[32:33]
	v_mul_f32_e32 v34, v59, v59
	v_pk_add_f32 v[32:33], v[34:35], v[32:33] op_sel_hi:[0,1]
	v_mul_f32_e32 v34, 0xbfb8aa3b, v206
	v_fma_f32 v35, v206, s43, -v34
	v_rndne_f32_e32 v36, v34
	v_fmac_f32_e32 v35, 0xb2a5705f, v206
	v_sub_f32_e32 v34, v34, v36
	v_add_f32_e32 v34, v34, v35
	v_exp_f32_e32 v34, v34
	v_cvt_i32_f32_e32 v35, v36
	v_ldexp_f32 v34, v34, v35
	v_mul_f32_e32 v35, 0xbfb8aa3b, v207
	v_fma_f32 v36, v207, s43, -v35
	v_rndne_f32_e32 v37, v35
	v_fmac_f32_e32 v36, 0xb2a5705f, v207
	v_sub_f32_e32 v35, v35, v37
	v_add_f32_e32 v35, v35, v36
	v_exp_f32_e32 v35, v35
	v_cvt_i32_f32_e32 v36, v37
	v_cndmask_b32_e32 v34, 0, v34, vcc
	v_cmp_ngt_f32_e32 vcc, s35, v206
	v_ldexp_f32 v35, v35, v36
	s_nop 0
	v_cndmask_b32_e32 v34, v179, v34, vcc
	v_cmp_nlt_f32_e32 vcc, s34, v207
	v_pk_fma_f32 v[36:37], v[40:41], v[124:125], v[202:203] op_sel_hi:[1,0,1]
	s_nop 0
	v_cndmask_b32_e32 v35, 0, v35, vcc
	v_cmp_ngt_f32_e32 vcc, s35, v207
	s_nop 1
	v_cndmask_b32_e32 v35, v179, v35, vcc
	v_pk_add_f32 v[34:35], v[34:35], 1.0 op_sel_hi:[1,0]
	s_nop 0
	v_div_scale_f32 v38, s[2:3], v35, v35, v207
	v_rcp_f32_e32 v39, v38
	s_nop 0
	v_fma_f32 v40, -v38, v39, 1.0
	v_fmac_f32_e32 v39, v40, v39
	v_div_scale_f32 v40, vcc, v207, v35, v207
	v_mul_f32_e32 v41, v40, v39
	v_fma_f32 v52, -v38, v41, v40
	v_fmac_f32_e32 v41, v52, v39
	v_fma_f32 v38, -v38, v41, v40
	v_div_fmas_f32 v38, v38, v39, v41
	v_div_fixup_f32 v35, v38, v35, v207
	v_div_scale_f32 v38, s[2:3], v34, v34, v206
	v_rcp_f32_e32 v39, v38
	s_nop 0
	v_fma_f32 v40, -v38, v39, 1.0
	v_fmac_f32_e32 v39, v40, v39
	v_div_scale_f32 v40, vcc, v206, v34, v206
	v_mul_f32_e32 v41, v40, v39
	v_fma_f32 v49, -v38, v41, v40
	v_fmac_f32_e32 v41, v49, v39
	v_fma_f32 v38, -v38, v41, v40
	v_div_fmas_f32 v38, v38, v39, v41
	v_div_fixup_f32 v34, v38, v34, v206
	v_pk_mul_f32 v[48:49], v[36:37], v[34:35]
	v_cmp_nlt_f32_e32 vcc, s34, v208
	v_pk_fma_f32 v[32:33], v[48:49], v[48:49], v[32:33]
	v_mul_f32_e32 v34, v49, v49
	v_pk_add_f32 v[32:33], v[34:35], v[32:33] op_sel_hi:[0,1]
	v_mul_f32_e32 v34, 0xbfb8aa3b, v208
	v_fma_f32 v35, v208, s43, -v34
	v_rndne_f32_e32 v36, v34
	v_fmac_f32_e32 v35, 0xb2a5705f, v208
	v_sub_f32_e32 v34, v34, v36
	v_add_f32_e32 v34, v34, v35
	v_exp_f32_e32 v34, v34
	v_cvt_i32_f32_e32 v35, v36
	v_ldexp_f32 v34, v34, v35
	v_mul_f32_e32 v35, 0xbfb8aa3b, v209
	v_fma_f32 v36, v209, s43, -v35
	v_rndne_f32_e32 v37, v35
	v_fmac_f32_e32 v36, 0xb2a5705f, v209
	v_sub_f32_e32 v35, v35, v37
	v_add_f32_e32 v35, v35, v36
	v_exp_f32_e32 v35, v35
	v_cvt_i32_f32_e32 v36, v37
	v_cndmask_b32_e32 v34, 0, v34, vcc
	v_cmp_ngt_f32_e32 vcc, s35, v208
	v_ldexp_f32 v35, v35, v36
	s_nop 0
	v_cndmask_b32_e32 v34, v179, v34, vcc
	v_cmp_nlt_f32_e32 vcc, s34, v209
	v_pk_fma_f32 v[36:37], v[42:43], v[124:125], v[204:205] op_sel_hi:[1,0,1]
	s_nop 0
	v_cndmask_b32_e32 v35, 0, v35, vcc
	v_cmp_ngt_f32_e32 vcc, s35, v209
	s_nop 1
	v_cndmask_b32_e32 v35, v179, v35, vcc
	v_pk_add_f32 v[34:35], v[34:35], 1.0 op_sel_hi:[1,0]
	s_nop 0
	v_div_scale_f32 v38, s[2:3], v35, v35, v209
	v_rcp_f32_e32 v39, v38
	s_nop 0
	v_fma_f32 v40, -v38, v39, 1.0
	v_fmac_f32_e32 v39, v40, v39
	v_div_scale_f32 v40, vcc, v209, v35, v209
	v_mul_f32_e32 v41, v40, v39
	v_fma_f32 v42, -v38, v41, v40
	v_fmac_f32_e32 v41, v42, v39
	v_fma_f32 v38, -v38, v41, v40
	v_div_fmas_f32 v38, v38, v39, v41
	v_div_fixup_f32 v35, v38, v35, v209
	v_div_scale_f32 v38, s[2:3], v34, v34, v208
	v_rcp_f32_e32 v39, v38
	s_nop 0
	v_fma_f32 v40, -v38, v39, 1.0
	v_fmac_f32_e32 v39, v40, v39
	v_div_scale_f32 v40, vcc, v208, v34, v208
	v_mul_f32_e32 v41, v40, v39
	v_fma_f32 v42, -v38, v41, v40
	v_fmac_f32_e32 v41, v42, v39
	v_fma_f32 v38, -v38, v41, v40
	v_div_fmas_f32 v38, v38, v39, v41
	v_div_fixup_f32 v34, v38, v34, v208
	v_pk_mul_f32 v[52:53], v[36:37], v[34:35]
	s_waitcnt vmcnt(0)
	v_cmp_nlt_f32_e32 vcc, s34, v214
	v_pk_fma_f32 v[32:33], v[52:53], v[52:53], v[32:33]
	v_mul_f32_e32 v34, v53, v53
	v_pk_add_f32 v[32:33], v[34:35], v[32:33] op_sel_hi:[0,1]
	v_mul_f32_e32 v34, 0xbfb8aa3b, v214
	v_fma_f32 v35, v214, s43, -v34
	v_rndne_f32_e32 v36, v34
	v_fmac_f32_e32 v35, 0xb2a5705f, v214
	v_sub_f32_e32 v34, v34, v36
	v_add_f32_e32 v34, v34, v35
	v_exp_f32_e32 v34, v34
	v_cvt_i32_f32_e32 v35, v36
	v_ldexp_f32 v34, v34, v35
	v_mul_f32_e32 v35, 0xbfb8aa3b, v215
	v_fma_f32 v36, v215, s43, -v35
	v_rndne_f32_e32 v37, v35
	v_fmac_f32_e32 v36, 0xb2a5705f, v215
	v_sub_f32_e32 v35, v35, v37
	v_add_f32_e32 v35, v35, v36
	v_exp_f32_e32 v35, v35
	v_cvt_i32_f32_e32 v36, v37
	v_cndmask_b32_e32 v34, 0, v34, vcc
	v_cmp_ngt_f32_e32 vcc, s35, v214
	v_ldexp_f32 v35, v35, v36
	s_nop 0
	v_cndmask_b32_e32 v34, v179, v34, vcc
	v_cmp_nlt_f32_e32 vcc, s34, v215
	v_pk_fma_f32 v[36:37], v[44:45], v[124:125], v[210:211] op_sel_hi:[1,0,1]
	s_nop 0
	v_cndmask_b32_e32 v35, 0, v35, vcc
	v_cmp_ngt_f32_e32 vcc, s35, v215
	s_nop 1
	v_cndmask_b32_e32 v35, v179, v35, vcc
	v_pk_add_f32 v[34:35], v[34:35], 1.0 op_sel_hi:[1,0]
	s_nop 0
	v_div_scale_f32 v38, s[2:3], v35, v35, v215
	v_rcp_f32_e32 v39, v38
	s_nop 0
	v_fma_f32 v40, -v38, v39, 1.0
	v_fmac_f32_e32 v39, v40, v39
	v_div_scale_f32 v40, vcc, v215, v35, v215
	v_mul_f32_e32 v41, v40, v39
	v_fma_f32 v42, -v38, v41, v40
	v_fmac_f32_e32 v41, v42, v39
	v_fma_f32 v38, -v38, v41, v40
	v_div_fmas_f32 v38, v38, v39, v41
	v_div_fixup_f32 v35, v38, v35, v215
	v_div_scale_f32 v38, s[2:3], v34, v34, v214
	v_rcp_f32_e32 v39, v38
	s_nop 0
	v_fma_f32 v40, -v38, v39, 1.0
	v_fmac_f32_e32 v39, v40, v39
	v_div_scale_f32 v40, vcc, v214, v34, v214
	v_mul_f32_e32 v41, v40, v39
	v_fma_f32 v42, -v38, v41, v40
	v_fmac_f32_e32 v41, v42, v39
	v_fma_f32 v38, -v38, v41, v40
	v_div_fmas_f32 v38, v38, v39, v41
	v_div_fixup_f32 v34, v38, v34, v214
	v_pk_mul_f32 v[60:61], v[36:37], v[34:35]
	v_cmp_nlt_f32_e32 vcc, s34, v216
	v_pk_fma_f32 v[32:33], v[60:61], v[60:61], v[32:33]
	v_mul_f32_e32 v34, v61, v61
	v_pk_add_f32 v[32:33], v[34:35], v[32:33] op_sel_hi:[0,1]
	v_mul_f32_e32 v34, 0xbfb8aa3b, v216
	v_fma_f32 v35, v216, s43, -v34
	v_rndne_f32_e32 v36, v34
	v_fmac_f32_e32 v35, 0xb2a5705f, v216
	v_sub_f32_e32 v34, v34, v36
	v_add_f32_e32 v34, v34, v35
	v_exp_f32_e32 v34, v34
	v_cvt_i32_f32_e32 v35, v36
	v_ldexp_f32 v34, v34, v35
	v_mul_f32_e32 v35, 0xbfb8aa3b, v217
	v_fma_f32 v36, v217, s43, -v35
	v_rndne_f32_e32 v37, v35
	v_fmac_f32_e32 v36, 0xb2a5705f, v217
	v_sub_f32_e32 v35, v35, v37
	v_add_f32_e32 v35, v35, v36
	v_exp_f32_e32 v35, v35
	v_cvt_i32_f32_e32 v36, v37
	v_cndmask_b32_e32 v34, 0, v34, vcc
	v_cmp_ngt_f32_e32 vcc, s35, v216
	v_ldexp_f32 v35, v35, v36
	s_nop 0
	v_cndmask_b32_e32 v34, v179, v34, vcc
	v_cmp_nlt_f32_e32 vcc, s34, v217
	v_pk_fma_f32 v[36:37], v[46:47], v[124:125], v[212:213] op_sel_hi:[1,0,1]
	s_nop 0
	v_cndmask_b32_e32 v35, 0, v35, vcc
	v_cmp_ngt_f32_e32 vcc, s35, v217
	s_nop 1
	v_cndmask_b32_e32 v35, v179, v35, vcc
	v_pk_add_f32 v[34:35], v[34:35], 1.0 op_sel_hi:[1,0]
	s_nop 0
	v_div_scale_f32 v38, s[2:3], v35, v35, v217
	v_rcp_f32_e32 v39, v38
	s_nop 0
	v_fma_f32 v40, -v38, v39, 1.0
	v_fmac_f32_e32 v39, v40, v39
	v_div_scale_f32 v40, vcc, v217, v35, v217
	v_mul_f32_e32 v41, v40, v39
	v_fma_f32 v42, -v38, v41, v40
	v_fmac_f32_e32 v41, v42, v39
	v_fma_f32 v38, -v38, v41, v40
	v_div_fmas_f32 v38, v38, v39, v41
	v_div_fixup_f32 v35, v38, v35, v217
	v_div_scale_f32 v38, s[2:3], v34, v34, v216
	v_rcp_f32_e32 v39, v38
	s_nop 0
	v_fma_f32 v40, -v38, v39, 1.0
	v_fmac_f32_e32 v39, v40, v39
	v_div_scale_f32 v40, vcc, v216, v34, v216
	v_mul_f32_e32 v41, v40, v39
	v_fma_f32 v42, -v38, v41, v40
	v_fmac_f32_e32 v41, v42, v39
	v_fma_f32 v38, -v38, v41, v40
	v_div_fmas_f32 v38, v38, v39, v41
	v_div_fixup_f32 v34, v38, v34, v216
	v_pk_mul_f32 v[78:79], v[36:37], v[34:35]
	s_nop 0
	v_pk_fma_f32 v[32:33], v[78:79], v[78:79], v[32:33]
	v_mul_f32_e32 v34, v79, v79
	v_pk_add_f32 v[32:33], v[34:35], v[32:33] op_sel_hi:[0,1]
	v_mov_b32_e32 v33, v32
	s_nop 1
	v_permlane32_swap_b32_e32 v32, v33
	s_and_saveexec_b64 s[14:15], s[48:49]
	v_add_f32_e32 v32, v32, v33
	ds_write_b32 v97, v32
	s_or_b64 exec, exec, s[14:15]
	v_mov_b32_e32 v33, s5
	v_or_b32_e32 v32, s4, v92
	v_lshlrev_b64 v[34:35], 5, v[32:33]
	v_lshl_add_u64 v[34:35], s[8:9], 0, v[34:35]
	global_load_dword v143, v[34:35], off
	v_mad_u64_u32 v[132:133], s[2:3], v32, s42, v[98:99]
	v_lshlrev_b64 v[50:51], 11, v[32:33]
	s_mul_i32 s2, s5, 0x2800
	v_lshl_add_u64 v[130:131], v[94:95], 0, v[50:51]
	v_add_u32_e32 v133, s2, v133
	global_load_dwordx4 v[70:73], v[130:131], off
	global_load_dwordx4 v[74:77], v[132:133], off
	global_load_dwordx4 v[134:137], v[130:131], off offset:32
	global_load_dwordx4 v[138:141], v[132:133], off offset:32
	global_load_dwordx4 v[44:47], v[130:131], off offset:64
	global_load_dwordx4 v[40:43], v[132:133], off offset:64
	global_load_dwordx4 v[36:39], v[130:131], off offset:96
	global_load_dwordx4 v[32:35], v[132:133], off offset:96
	global_load_dwordx4 v[186:189], v[130:131], off offset:128
	global_load_dwordx4 v[190:193], v[132:133], off offset:128
	global_load_dwordx4 v[194:197], v[130:131], off offset:160
	global_load_dwordx4 v[198:201], v[132:133], off offset:160
	global_load_dwordx4 v[202:205], v[130:131], off offset:192
	global_load_dwordx4 v[206:209], v[132:133], off offset:192
	global_load_dwordx4 v[210:213], v[130:131], off offset:224
	global_load_dwordx4 v[214:217], v[132:133], off offset:224
	s_waitcnt vmcnt(16)
	v_exp_f32_e32 v126, v143
	s_waitcnt vmcnt(15)
	v_pk_fma_f32 v[16:17], v[16:17], v[126:127], v[70:71] op_sel_hi:[1,0,1]
	v_pk_fma_f32 v[18:19], v[18:19], v[126:127], v[72:73] op_sel_hi:[1,0,1]
	s_waitcnt vmcnt(14)
	v_mul_f32_e32 v54, 0xbfb8aa3b, v74
	v_fma_f32 v55, v74, s43, -v54
	v_rndne_f32_e32 v62, v54
	v_fmac_f32_e32 v55, 0xb2a5705f, v74
	v_sub_f32_e32 v54, v54, v62
	v_add_f32_e32 v54, v54, v55
	v_exp_f32_e32 v54, v54
	v_cvt_i32_f32_e32 v55, v62
	v_cmp_nlt_f32_e32 vcc, s34, v74
	s_waitcnt vmcnt(13)
	v_pk_fma_f32 v[20:21], v[20:21], v[126:127], v[134:135] op_sel_hi:[1,0,1]
	v_ldexp_f32 v54, v54, v55
	v_mul_f32_e32 v55, 0xbfb8aa3b, v75
	v_fma_f32 v62, v75, s43, -v55
	v_rndne_f32_e32 v63, v55
	v_fmac_f32_e32 v62, 0xb2a5705f, v75
	v_sub_f32_e32 v55, v55, v63
	v_add_f32_e32 v55, v55, v62
	v_exp_f32_e32 v55, v55
	v_cvt_i32_f32_e32 v62, v63
	v_cndmask_b32_e32 v54, 0, v54, vcc
	v_cmp_ngt_f32_e32 vcc, s35, v74
	v_ldexp_f32 v55, v55, v62
	s_nop 0
	v_cndmask_b32_e32 v54, v179, v54, vcc
	v_cmp_nlt_f32_e32 vcc, s34, v75
	s_nop 1
	v_cndmask_b32_e32 v55, 0, v55, vcc
	v_cmp_ngt_f32_e32 vcc, s35, v75
	s_nop 1
	v_cndmask_b32_e32 v55, v179, v55, vcc
	v_pk_add_f32 v[54:55], v[54:55], 1.0 op_sel_hi:[1,0]
	s_nop 0
	v_div_scale_f32 v62, s[2:3], v55, v55, v75
	v_rcp_f32_e32 v63, v62
	s_nop 0
	v_fma_f32 v68, -v62, v63, 1.0
	v_fmac_f32_e32 v63, v68, v63
	v_div_scale_f32 v68, vcc, v75, v55, v75
	v_mul_f32_e32 v69, v68, v63
	v_fma_f32 v70, -v62, v69, v68
	v_fmac_f32_e32 v69, v70, v63
	v_fma_f32 v62, -v62, v69, v68
	v_div_fmas_f32 v62, v62, v63, v69
	v_div_fixup_f32 v55, v62, v55, v75
	v_div_scale_f32 v62, s[2:3], v54, v54, v74
	v_rcp_f32_e32 v63, v62
	s_nop 0
	v_fma_f32 v68, -v62, v63, 1.0
	v_fmac_f32_e32 v63, v68, v63
	v_div_scale_f32 v68, vcc, v74, v54, v74
	v_mul_f32_e32 v69, v68, v63
	v_fma_f32 v70, -v62, v69, v68
	v_fmac_f32_e32 v69, v70, v63
	v_fma_f32 v62, -v62, v69, v68
	v_div_fmas_f32 v62, v62, v63, v69
	v_div_fixup_f32 v54, v62, v54, v74
	v_pk_mul_f32 v[70:71], v[16:17], v[54:55]
	v_mul_f32_e32 v54, 0xbfb8aa3b, v76
	v_fma_f32 v55, v76, s43, -v54
	v_rndne_f32_e32 v62, v54
	v_fmac_f32_e32 v55, 0xb2a5705f, v76
	v_sub_f32_e32 v54, v54, v62
	v_add_f32_e32 v54, v54, v55
	v_exp_f32_e32 v54, v54
	v_cvt_i32_f32_e32 v55, v62
	v_cmp_nlt_f32_e32 vcc, s34, v76
	v_mul_f32_e32 v16, v71, v71
	v_pk_fma_f32 v[16:17], v[70:71], v[70:71], v[16:17] op_sel_hi:[1,1,0]
	v_ldexp_f32 v54, v54, v55
	v_mul_f32_e32 v55, 0xbfb8aa3b, v77
	v_fma_f32 v62, v77, s43, -v55
	v_rndne_f32_e32 v63, v55
	v_fmac_f32_e32 v62, 0xb2a5705f, v77
	v_sub_f32_e32 v55, v55, v63
	v_add_f32_e32 v55, v55, v62
	v_exp_f32_e32 v55, v55
	v_cvt_i32_f32_e32 v62, v63
	v_cndmask_b32_e32 v54, 0, v54, vcc
	v_cmp_ngt_f32_e32 vcc, s35, v76
	v_ldexp_f32 v55, v55, v62
	s_nop 0
	v_cndmask_b32_e32 v54, v179, v54, vcc
	v_cmp_nlt_f32_e32 vcc, s34, v77
	s_nop 1
	v_cndmask_b32_e32 v55, 0, v55, vcc
	v_cmp_ngt_f32_e32 vcc, s35, v77
	s_nop 1
	v_cndmask_b32_e32 v55, v179, v55, vcc
	v_pk_add_f32 v[54:55], v[54:55], 1.0 op_sel_hi:[1,0]
	s_nop 0
	v_div_scale_f32 v62, s[2:3], v55, v55, v77
	v_rcp_f32_e32 v63, v62
	s_nop 0
	v_fma_f32 v68, -v62, v63, 1.0
	v_fmac_f32_e32 v63, v68, v63
	v_div_scale_f32 v68, vcc, v77, v55, v77
	v_mul_f32_e32 v69, v68, v63
	v_fma_f32 v72, -v62, v69, v68
	v_fmac_f32_e32 v69, v72, v63
	v_fma_f32 v62, -v62, v69, v68
	v_div_fmas_f32 v62, v62, v63, v69
	v_div_fixup_f32 v55, v62, v55, v77
	v_div_scale_f32 v62, s[2:3], v54, v54, v76
	v_rcp_f32_e32 v63, v62
	s_nop 0
	v_fma_f32 v68, -v62, v63, 1.0
	v_fmac_f32_e32 v63, v68, v63
	v_div_scale_f32 v68, vcc, v76, v54, v76
	v_mul_f32_e32 v69, v68, v63
	v_fma_f32 v72, -v62, v69, v68
	v_fmac_f32_e32 v69, v72, v63
	v_fma_f32 v62, -v62, v69, v68
	v_div_fmas_f32 v62, v62, v63, v69
	v_div_fixup_f32 v54, v62, v54, v76
	v_pk_mul_f32 v[74:75], v[18:19], v[54:55]
	s_waitcnt vmcnt(12)
	v_cmp_nlt_f32_e32 vcc, s34, v138
	v_pk_fma_f32 v[16:17], v[74:75], v[74:75], v[16:17]
	v_mul_f32_e32 v18, v75, v75
	v_pk_add_f32 v[16:17], v[18:19], v[16:17] op_sel_hi:[0,1]
	v_mul_f32_e32 v18, 0xbfb8aa3b, v138
	v_fma_f32 v19, v138, s43, -v18
	v_rndne_f32_e32 v54, v18
	v_fmac_f32_e32 v19, 0xb2a5705f, v138
	v_sub_f32_e32 v18, v18, v54
	v_add_f32_e32 v18, v18, v19
	v_exp_f32_e32 v18, v18
	v_cvt_i32_f32_e32 v19, v54
	v_ldexp_f32 v18, v18, v19
	v_mul_f32_e32 v19, 0xbfb8aa3b, v139
	v_fma_f32 v54, v139, s43, -v19
	v_rndne_f32_e32 v55, v19
	v_fmac_f32_e32 v54, 0xb2a5705f, v139
	v_sub_f32_e32 v19, v19, v55
	v_add_f32_e32 v19, v19, v54
	v_exp_f32_e32 v19, v19
	v_cvt_i32_f32_e32 v54, v55
	v_cndmask_b32_e32 v18, 0, v18, vcc
	v_cmp_ngt_f32_e32 vcc, s35, v138
	v_ldexp_f32 v19, v19, v54
	s_nop 0
	v_cndmask_b32_e32 v18, v179, v18, vcc
	v_cmp_nlt_f32_e32 vcc, s34, v139
	s_nop 1
	v_cndmask_b32_e32 v19, 0, v19, vcc
	v_cmp_ngt_f32_e32 vcc, s35, v139
	s_nop 1
	v_cndmask_b32_e32 v19, v179, v19, vcc
	v_pk_add_f32 v[18:19], v[18:19], 1.0 op_sel_hi:[1,0]
	s_nop 0
	v_div_scale_f32 v54, s[2:3], v19, v19, v139
	v_rcp_f32_e32 v55, v54
	s_nop 0
	v_fma_f32 v62, -v54, v55, 1.0
	v_fmac_f32_e32 v55, v62, v55
	v_div_scale_f32 v62, vcc, v139, v19, v139
	v_mul_f32_e32 v63, v62, v55
	v_fma_f32 v68, -v54, v63, v62
	v_fmac_f32_e32 v63, v68, v55
	v_fma_f32 v54, -v54, v63, v62
	v_div_fmas_f32 v54, v54, v55, v63
	v_div_fixup_f32 v19, v54, v19, v139
	v_div_scale_f32 v54, s[2:3], v18, v18, v138
	v_rcp_f32_e32 v55, v54
	s_nop 0
	v_fma_f32 v62, -v54, v55, 1.0
	v_fmac_f32_e32 v55, v62, v55
	v_div_scale_f32 v62, vcc, v138, v18, v138
	v_mul_f32_e32 v63, v62, v55
	v_fma_f32 v68, -v54, v63, v62
	v_fmac_f32_e32 v63, v68, v55
	v_fma_f32 v54, -v54, v63, v62
	v_div_fmas_f32 v54, v54, v55, v63
	v_div_fixup_f32 v18, v54, v18, v138
	v_pk_mul_f32 v[54:55], v[20:21], v[18:19]
	v_cmp_nlt_f32_e32 vcc, s34, v140
	v_pk_fma_f32 v[16:17], v[54:55], v[54:55], v[16:17]
	v_mul_f32_e32 v18, v55, v55
	v_pk_add_f32 v[16:17], v[18:19], v[16:17] op_sel_hi:[0,1]
	v_mul_f32_e32 v18, 0xbfb8aa3b, v140
	v_fma_f32 v19, v140, s43, -v18
	v_rndne_f32_e32 v20, v18
	v_fmac_f32_e32 v19, 0xb2a5705f, v140
	v_sub_f32_e32 v18, v18, v20
	v_add_f32_e32 v18, v18, v19
	v_exp_f32_e32 v18, v18
	v_cvt_i32_f32_e32 v19, v20
	v_ldexp_f32 v18, v18, v19
	v_mul_f32_e32 v19, 0xbfb8aa3b, v141
	v_fma_f32 v20, v141, s43, -v19
	v_rndne_f32_e32 v21, v19
	v_fmac_f32_e32 v20, 0xb2a5705f, v141
	v_sub_f32_e32 v19, v19, v21
	v_add_f32_e32 v19, v19, v20
	v_exp_f32_e32 v19, v19
	v_cvt_i32_f32_e32 v20, v21
	v_cndmask_b32_e32 v18, 0, v18, vcc
	v_cmp_ngt_f32_e32 vcc, s35, v140
	v_ldexp_f32 v19, v19, v20
	s_nop 0
	v_cndmask_b32_e32 v18, v179, v18, vcc
	v_cmp_nlt_f32_e32 vcc, s34, v141
	v_pk_fma_f32 v[20:21], v[22:23], v[126:127], v[136:137] op_sel_hi:[1,0,1]
	s_nop 0
	v_cndmask_b32_e32 v19, 0, v19, vcc
	v_cmp_ngt_f32_e32 vcc, s35, v141
	s_nop 1
	v_cndmask_b32_e32 v19, v179, v19, vcc
	v_pk_add_f32 v[18:19], v[18:19], 1.0 op_sel_hi:[1,0]
	s_nop 0
	v_div_scale_f32 v22, s[2:3], v19, v19, v141
	v_rcp_f32_e32 v23, v22
	s_nop 0
	v_fma_f32 v62, -v22, v23, 1.0
	v_fmac_f32_e32 v23, v62, v23
	v_div_scale_f32 v62, vcc, v141, v19, v141
	v_mul_f32_e32 v63, v62, v23
	v_fma_f32 v68, -v22, v63, v62
	v_fmac_f32_e32 v63, v68, v23
	v_fma_f32 v22, -v22, v63, v62
	v_div_fmas_f32 v22, v22, v23, v63
	v_div_fixup_f32 v19, v22, v19, v141
	v_div_scale_f32 v22, s[2:3], v18, v18, v140
	v_rcp_f32_e32 v23, v22
	s_nop 0
	v_fma_f32 v62, -v22, v23, 1.0
	v_fmac_f32_e32 v23, v62, v23
	v_div_scale_f32 v62, vcc, v140, v18, v140
	v_mul_f32_e32 v63, v62, v23
	v_fma_f32 v68, -v22, v63, v62
	v_fmac_f32_e32 v63, v68, v23
	v_fma_f32 v22, -v22, v63, v62
	v_div_fmas_f32 v22, v22, v23, v63
	v_div_fixup_f32 v18, v22, v18, v140
	v_pk_mul_f32 v[62:63], v[20:21], v[18:19]
	s_waitcnt vmcnt(10)
	v_cmp_nlt_f32_e32 vcc, s34, v40
	v_pk_fma_f32 v[16:17], v[62:63], v[62:63], v[16:17]
	v_mul_f32_e32 v18, v63, v63
	v_pk_add_f32 v[16:17], v[18:19], v[16:17] op_sel_hi:[0,1]
	v_mul_f32_e32 v18, 0xbfb8aa3b, v40
	v_fma_f32 v19, v40, s43, -v18
	v_rndne_f32_e32 v20, v18
	v_fmac_f32_e32 v19, 0xb2a5705f, v40
	v_sub_f32_e32 v18, v18, v20
	v_add_f32_e32 v18, v18, v19
	v_exp_f32_e32 v18, v18
	v_cvt_i32_f32_e32 v19, v20
	v_ldexp_f32 v18, v18, v19
	v_mul_f32_e32 v19, 0xbfb8aa3b, v41
	v_fma_f32 v20, v41, s43, -v19
	v_rndne_f32_e32 v21, v19
	v_fmac_f32_e32 v20, 0xb2a5705f, v41
	v_sub_f32_e32 v19, v19, v21
	v_add_f32_e32 v19, v19, v20
	v_exp_f32_e32 v19, v19
	v_cvt_i32_f32_e32 v20, v21
	v_cndmask_b32_e32 v18, 0, v18, vcc
	v_cmp_ngt_f32_e32 vcc, s35, v40
	v_ldexp_f32 v19, v19, v20
	s_nop 0
	v_cndmask_b32_e32 v18, v179, v18, vcc
	v_cmp_nlt_f32_e32 vcc, s34, v41
	v_pk_fma_f32 v[20:21], v[24:25], v[126:127], v[44:45] op_sel_hi:[1,0,1]
	s_nop 0
	v_cndmask_b32_e32 v19, 0, v19, vcc
	v_cmp_ngt_f32_e32 vcc, s35, v41
	s_nop 1
	v_cndmask_b32_e32 v19, v179, v19, vcc
	v_pk_add_f32 v[18:19], v[18:19], 1.0 op_sel_hi:[1,0]
	s_nop 0
	v_div_scale_f32 v22, s[2:3], v19, v19, v41
	v_rcp_f32_e32 v23, v22
	s_nop 0
	v_fma_f32 v24, -v22, v23, 1.0
	v_fmac_f32_e32 v23, v24, v23
	v_div_scale_f32 v24, vcc, v41, v19, v41
	v_mul_f32_e32 v25, v24, v23
	v_fma_f32 v44, -v22, v25, v24
	v_fmac_f32_e32 v25, v44, v23
	v_fma_f32 v22, -v22, v25, v24
	v_div_fmas_f32 v22, v22, v23, v25
	v_div_fixup_f32 v19, v22, v19, v41
	v_div_scale_f32 v22, s[2:3], v18, v18, v40
	v_rcp_f32_e32 v23, v22
	s_nop 0
	v_fma_f32 v24, -v22, v23, 1.0
	v_fmac_f32_e32 v23, v24, v23
	v_div_scale_f32 v24, vcc, v40, v18, v40
	v_mul_f32_e32 v25, v24, v23
	v_fma_f32 v41, -v22, v25, v24
	v_fmac_f32_e32 v25, v41, v23
	v_fma_f32 v22, -v22, v25, v24
	v_div_fmas_f32 v22, v22, v23, v25
	v_div_fixup_f32 v18, v22, v18, v40
	v_pk_mul_f32 v[68:69], v[20:21], v[18:19]
	v_cmp_nlt_f32_e32 vcc, s34, v42
	v_pk_fma_f32 v[16:17], v[68:69], v[68:69], v[16:17]
	v_mul_f32_e32 v18, v69, v69
	v_pk_add_f32 v[16:17], v[18:19], v[16:17] op_sel_hi:[0,1]
	v_mul_f32_e32 v18, 0xbfb8aa3b, v42
	v_fma_f32 v19, v42, s43, -v18
	v_rndne_f32_e32 v20, v18
	v_fmac_f32_e32 v19, 0xb2a5705f, v42
	v_sub_f32_e32 v18, v18, v20
	v_add_f32_e32 v18, v18, v19
	v_exp_f32_e32 v18, v18
	v_cvt_i32_f32_e32 v19, v20
	v_ldexp_f32 v18, v18, v19
	v_mul_f32_e32 v19, 0xbfb8aa3b, v43
	v_fma_f32 v20, v43, s43, -v19
	v_rndne_f32_e32 v21, v19
	v_fmac_f32_e32 v20, 0xb2a5705f, v43
	v_sub_f32_e32 v19, v19, v21
	v_add_f32_e32 v19, v19, v20
	v_exp_f32_e32 v19, v19
	v_cvt_i32_f32_e32 v20, v21
	v_cndmask_b32_e32 v18, 0, v18, vcc
	v_cmp_ngt_f32_e32 vcc, s35, v42
	v_ldexp_f32 v19, v19, v20
	s_nop 0
	v_cndmask_b32_e32 v18, v179, v18, vcc
	v_cmp_nlt_f32_e32 vcc, s34, v43
	v_pk_fma_f32 v[20:21], v[26:27], v[126:127], v[46:47] op_sel_hi:[1,0,1]
	s_nop 0
	v_cndmask_b32_e32 v19, 0, v19, vcc
	v_cmp_ngt_f32_e32 vcc, s35, v43
	s_nop 1
	v_cndmask_b32_e32 v19, v179, v19, vcc
	v_pk_add_f32 v[18:19], v[18:19], 1.0 op_sel_hi:[1,0]
	s_nop 0
	v_div_scale_f32 v22, s[2:3], v19, v19, v43
	v_rcp_f32_e32 v23, v22
	s_nop 0
	v_fma_f32 v24, -v22, v23, 1.0
	v_fmac_f32_e32 v23, v24, v23
	v_div_scale_f32 v24, vcc, v43, v19, v43
	v_mul_f32_e32 v25, v24, v23
	v_fma_f32 v26, -v22, v25, v24
	v_fmac_f32_e32 v25, v26, v23
	v_fma_f32 v22, -v22, v25, v24
	v_div_fmas_f32 v22, v22, v23, v25
	v_div_fixup_f32 v19, v22, v19, v43
	v_div_scale_f32 v22, s[2:3], v18, v18, v42
	v_rcp_f32_e32 v23, v22
	s_nop 0
	v_fma_f32 v24, -v22, v23, 1.0
	v_fmac_f32_e32 v23, v24, v23
	v_div_scale_f32 v24, vcc, v42, v18, v42
	v_mul_f32_e32 v25, v24, v23
	v_fma_f32 v26, -v22, v25, v24
	v_fmac_f32_e32 v25, v26, v23
	v_fma_f32 v22, -v22, v25, v24
	v_div_fmas_f32 v22, v22, v23, v25
	v_div_fixup_f32 v18, v22, v18, v42
	v_pk_mul_f32 v[72:73], v[20:21], v[18:19]
	s_waitcnt vmcnt(8)
	v_cmp_nlt_f32_e32 vcc, s34, v32
	v_pk_fma_f32 v[16:17], v[72:73], v[72:73], v[16:17]
	v_mul_f32_e32 v18, v73, v73
	v_pk_add_f32 v[16:17], v[18:19], v[16:17] op_sel_hi:[0,1]
	v_mul_f32_e32 v18, 0xbfb8aa3b, v32
	v_fma_f32 v19, v32, s43, -v18
	v_rndne_f32_e32 v20, v18
	v_fmac_f32_e32 v19, 0xb2a5705f, v32
	v_sub_f32_e32 v18, v18, v20
	v_add_f32_e32 v18, v18, v19
	v_exp_f32_e32 v18, v18
	v_cvt_i32_f32_e32 v19, v20
	v_ldexp_f32 v18, v18, v19
	v_mul_f32_e32 v19, 0xbfb8aa3b, v33
	v_fma_f32 v20, v33, s43, -v19
	v_rndne_f32_e32 v21, v19
	v_fmac_f32_e32 v20, 0xb2a5705f, v33
	v_sub_f32_e32 v19, v19, v21
	v_add_f32_e32 v19, v19, v20
	v_exp_f32_e32 v19, v19
	v_cvt_i32_f32_e32 v20, v21
	v_cndmask_b32_e32 v18, 0, v18, vcc
	v_cmp_ngt_f32_e32 vcc, s35, v32
	v_ldexp_f32 v19, v19, v20
	s_nop 0
	v_cndmask_b32_e32 v18, v179, v18, vcc
	v_cmp_nlt_f32_e32 vcc, s34, v33
	v_pk_fma_f32 v[20:21], v[28:29], v[126:127], v[36:37] op_sel_hi:[1,0,1]
	s_nop 0
	v_cndmask_b32_e32 v19, 0, v19, vcc
	v_cmp_ngt_f32_e32 vcc, s35, v33
	s_nop 1
	v_cndmask_b32_e32 v19, v179, v19, vcc
	v_pk_add_f32 v[18:19], v[18:19], 1.0 op_sel_hi:[1,0]
	s_nop 0
	v_div_scale_f32 v22, s[2:3], v19, v19, v33
	v_rcp_f32_e32 v23, v22
	s_nop 0
	v_fma_f32 v24, -v22, v23, 1.0
	v_fmac_f32_e32 v23, v24, v23
	v_div_scale_f32 v24, vcc, v33, v19, v33
	v_mul_f32_e32 v25, v24, v23
	v_fma_f32 v26, -v22, v25, v24
	v_fmac_f32_e32 v25, v26, v23
	v_fma_f32 v22, -v22, v25, v24
	v_div_fmas_f32 v22, v22, v23, v25
	v_div_fixup_f32 v19, v22, v19, v33
	v_div_scale_f32 v22, s[2:3], v18, v18, v32
	v_rcp_f32_e32 v23, v22
	s_nop 0
	v_fma_f32 v24, -v22, v23, 1.0
	v_fmac_f32_e32 v23, v24, v23
	v_div_scale_f32 v24, vcc, v32, v18, v32
	v_mul_f32_e32 v25, v24, v23
	v_fma_f32 v26, -v22, v25, v24
	v_fmac_f32_e32 v25, v26, v23
	v_fma_f32 v22, -v22, v25, v24
	v_div_fmas_f32 v22, v22, v23, v25
	v_div_fixup_f32 v18, v22, v18, v32
	v_pk_mul_f32 v[76:77], v[20:21], v[18:19]
	v_cmp_nlt_f32_e32 vcc, s34, v34
	v_pk_fma_f32 v[16:17], v[76:77], v[76:77], v[16:17]
	v_mul_f32_e32 v18, v77, v77
	v_pk_add_f32 v[16:17], v[18:19], v[16:17] op_sel_hi:[0,1]
	v_mul_f32_e32 v18, 0xbfb8aa3b, v34
	v_fma_f32 v19, v34, s43, -v18
	v_rndne_f32_e32 v20, v18
	v_fmac_f32_e32 v19, 0xb2a5705f, v34
	v_sub_f32_e32 v18, v18, v20
	v_add_f32_e32 v18, v18, v19
	v_exp_f32_e32 v18, v18
	v_cvt_i32_f32_e32 v19, v20
	v_ldexp_f32 v18, v18, v19
	v_mul_f32_e32 v19, 0xbfb8aa3b, v35
	v_fma_f32 v20, v35, s43, -v19
	v_rndne_f32_e32 v21, v19
	v_fmac_f32_e32 v20, 0xb2a5705f, v35
	v_sub_f32_e32 v19, v19, v21
	v_add_f32_e32 v19, v19, v20
	v_exp_f32_e32 v19, v19
	v_cvt_i32_f32_e32 v20, v21
	v_cndmask_b32_e32 v18, 0, v18, vcc
	v_cmp_ngt_f32_e32 vcc, s35, v34
	v_ldexp_f32 v19, v19, v20
	s_nop 0
	v_cndmask_b32_e32 v18, v179, v18, vcc
	v_cmp_nlt_f32_e32 vcc, s34, v35
	v_pk_fma_f32 v[20:21], v[30:31], v[126:127], v[38:39] op_sel_hi:[1,0,1]
	s_nop 0
	v_cndmask_b32_e32 v19, 0, v19, vcc
	v_cmp_ngt_f32_e32 vcc, s35, v35
	s_nop 1
	v_cndmask_b32_e32 v19, v179, v19, vcc
	v_pk_add_f32 v[18:19], v[18:19], 1.0 op_sel_hi:[1,0]
	s_nop 0
	v_div_scale_f32 v22, s[2:3], v19, v19, v35
	v_rcp_f32_e32 v23, v22
	s_nop 0
	v_fma_f32 v24, -v22, v23, 1.0
	v_fmac_f32_e32 v23, v24, v23
	v_div_scale_f32 v24, vcc, v35, v19, v35
	v_mul_f32_e32 v25, v24, v23
	v_fma_f32 v26, -v22, v25, v24
	v_fmac_f32_e32 v25, v26, v23
	v_fma_f32 v22, -v22, v25, v24
	v_div_fmas_f32 v22, v22, v23, v25
	v_div_fixup_f32 v19, v22, v19, v35
	v_div_scale_f32 v22, s[2:3], v18, v18, v34
	v_rcp_f32_e32 v23, v22
	s_nop 0
	v_fma_f32 v24, -v22, v23, 1.0
	v_fmac_f32_e32 v23, v24, v23
	v_div_scale_f32 v24, vcc, v34, v18, v34
	v_mul_f32_e32 v25, v24, v23
	v_fma_f32 v26, -v22, v25, v24
	v_fmac_f32_e32 v25, v26, v23
	v_fma_f32 v22, -v22, v25, v24
	v_div_fmas_f32 v22, v22, v23, v25
	v_div_fixup_f32 v18, v22, v18, v34
	v_pk_mul_f32 v[124:125], v[20:21], v[18:19]
	s_nop 0
	v_pk_fma_f32 v[16:17], v[124:125], v[124:125], v[16:17]
	v_mul_f32_e32 v18, v125, v125
	v_pk_add_f32 v[128:129], v[18:19], v[16:17] op_sel_hi:[0,1]
	s_waitcnt vmcnt(7)
	v_pk_fma_f32 v[0:1], v[0:1], v[126:127], v[186:187] op_sel_hi:[1,0,1]
	s_waitcnt vmcnt(6)
	v_mul_f32_e32 v103, 0xbfb8aa3b, v190
	v_fma_f32 v105, v190, s43, -v103
	v_rndne_f32_e32 v107, v103
	v_fmac_f32_e32 v105, 0xb2a5705f, v190
	v_sub_f32_e32 v103, v103, v107
	v_add_f32_e32 v103, v103, v105
	v_exp_f32_e32 v103, v103
	v_cvt_i32_f32_e32 v105, v107
	v_cmp_nlt_f32_e32 vcc, s34, v190
	v_ldexp_f32 v103, v103, v105
	s_nop 0
	v_cndmask_b32_e32 v103, 0, v103, vcc
	v_cmp_ngt_f32_e32 vcc, s35, v190
	s_nop 1
	v_cndmask_b32_e32 v130, v179, v103, vcc
	v_mul_f32_e32 v103, 0xbfb8aa3b, v191
	v_fma_f32 v105, v191, s43, -v103
	v_rndne_f32_e32 v107, v103
	v_fmac_f32_e32 v105, 0xb2a5705f, v191
	v_sub_f32_e32 v103, v103, v107
	v_add_f32_e32 v103, v103, v105
	v_exp_f32_e32 v103, v103
	v_cvt_i32_f32_e32 v105, v107
	v_cmp_nlt_f32_e32 vcc, s34, v191
	v_ldexp_f32 v103, v103, v105
	s_nop 0
	v_cndmask_b32_e32 v103, 0, v103, vcc
	v_cmp_ngt_f32_e32 vcc, s35, v191
	s_nop 1
	v_cndmask_b32_e32 v131, v179, v103, vcc
	v_pk_add_f32 v[36:37], v[130:131], 1.0 op_sel_hi:[1,0]
	s_nop 0
	v_div_scale_f32 v103, s[2:3], v37, v37, v191
	v_rcp_f32_e32 v105, v103
	s_nop 0
	v_fma_f32 v107, -v103, v105, 1.0
	v_fmac_f32_e32 v105, v107, v105
	v_div_scale_f32 v107, vcc, v191, v37, v191
	v_mul_f32_e32 v109, v107, v105
	v_fma_f32 v127, -v103, v109, v107
	v_fmac_f32_e32 v109, v127, v105
	v_fma_f32 v103, -v103, v109, v107
	v_div_fmas_f32 v103, v103, v105, v109
	v_div_fixup_f32 v33, v103, v37, v191
	v_div_scale_f32 v37, s[2:3], v36, v36, v190
	v_rcp_f32_e32 v103, v37
	v_pk_fma_f32 v[2:3], v[2:3], v[126:127], v[188:189] op_sel_hi:[1,0,1]
	s_waitcnt vmcnt(5)
	v_pk_fma_f32 v[4:5], v[4:5], v[126:127], v[194:195] op_sel_hi:[1,0,1]
	v_pk_fma_f32 v[6:7], v[6:7], v[126:127], v[196:197] op_sel_hi:[1,0,1]
	v_fma_f32 v105, -v37, v103, 1.0
	v_fmac_f32_e32 v103, v105, v103
	v_div_scale_f32 v105, vcc, v190, v36, v190
	v_mul_f32_e32 v107, v105, v103
	v_fma_f32 v109, -v37, v107, v105
	v_fmac_f32_e32 v107, v109, v103
	v_fma_f32 v37, -v37, v107, v105
	v_div_fmas_f32 v37, v37, v103, v107
	v_div_fixup_f32 v32, v37, v36, v190
	v_pk_mul_f32 v[0:1], v[0:1], v[32:33]
	v_cmp_nlt_f32_e32 vcc, s34, v192
	v_pk_fma_f32 v[32:33], v[0:1], v[0:1], v[128:129]
	v_mul_f32_e32 v36, v1, v1
	v_pk_add_f32 v[32:33], v[36:37], v[32:33] op_sel_hi:[0,1]
	v_mul_f32_e32 v36, 0xbfb8aa3b, v192
	v_fma_f32 v37, v192, s43, -v36
	v_rndne_f32_e32 v103, v36
	v_fmac_f32_e32 v37, 0xb2a5705f, v192
	v_sub_f32_e32 v36, v36, v103
	v_add_f32_e32 v36, v36, v37
	v_exp_f32_e32 v36, v36
	v_cvt_i32_f32_e32 v37, v103
	s_waitcnt vmcnt(3)
	v_pk_fma_f32 v[8:9], v[8:9], v[126:127], v[202:203] op_sel_hi:[1,0,1]
	v_pk_fma_f32 v[10:11], v[10:11], v[126:127], v[204:205] op_sel_hi:[1,0,1]
	s_waitcnt vmcnt(1)
	v_pk_fma_f32 v[12:13], v[12:13], v[126:127], v[210:211] op_sel_hi:[1,0,1]
	v_ldexp_f32 v36, v36, v37
	v_mul_f32_e32 v37, 0xbfb8aa3b, v193
	v_fma_f32 v103, v193, s43, -v37
	v_rndne_f32_e32 v105, v37
	v_fmac_f32_e32 v103, 0xb2a5705f, v193
	v_sub_f32_e32 v37, v37, v105
	v_add_f32_e32 v37, v37, v103
	v_exp_f32_e32 v37, v37
	v_cvt_i32_f32_e32 v103, v105
	v_cndmask_b32_e32 v36, 0, v36, vcc
	v_cmp_ngt_f32_e32 vcc, s35, v192
	v_pk_fma_f32 v[14:15], v[14:15], v[126:127], v[212:213] op_sel_hi:[1,0,1]
	v_ldexp_f32 v37, v37, v103
	v_cndmask_b32_e32 v36, v179, v36, vcc
	v_cmp_nlt_f32_e32 vcc, s34, v193
	s_nop 1
	v_cndmask_b32_e32 v37, 0, v37, vcc
	v_cmp_ngt_f32_e32 vcc, s35, v193
	s_nop 1
	v_cndmask_b32_e32 v37, v179, v37, vcc
	v_pk_add_f32 v[36:37], v[36:37], 1.0 op_sel_hi:[1,0]
	s_nop 0
	v_div_scale_f32 v38, s[2:3], v37, v37, v193
	v_rcp_f32_e32 v39, v38
	s_nop 0
	v_fma_f32 v103, -v38, v39, 1.0
	v_fmac_f32_e32 v39, v103, v39
	v_div_scale_f32 v103, vcc, v193, v37, v193
	v_mul_f32_e32 v105, v103, v39
	v_fma_f32 v107, -v38, v105, v103
	v_fmac_f32_e32 v105, v107, v39
	v_fma_f32 v38, -v38, v105, v103
	v_div_fmas_f32 v38, v38, v39, v105
	v_div_fixup_f32 v35, v38, v37, v193
	v_div_scale_f32 v37, s[2:3], v36, v36, v192
	v_rcp_f32_e32 v38, v37
	s_nop 0
	v_fma_f32 v39, -v37, v38, 1.0
	v_fmac_f32_e32 v38, v39, v38
	v_div_scale_f32 v39, vcc, v192, v36, v192
	v_mul_f32_e32 v103, v39, v38
	v_fma_f32 v105, -v37, v103, v39
	v_fmac_f32_e32 v103, v105, v38
	v_fma_f32 v37, -v37, v103, v39
	v_div_fmas_f32 v37, v37, v38, v103
	v_div_fixup_f32 v34, v37, v36, v192
	v_pk_mul_f32 v[2:3], v[2:3], v[34:35]
	v_cmp_nlt_f32_e32 vcc, s34, v198
	v_pk_fma_f32 v[32:33], v[2:3], v[2:3], v[32:33]
	v_mul_f32_e32 v34, v3, v3
	v_pk_add_f32 v[32:33], v[34:35], v[32:33] op_sel_hi:[0,1]
	v_mul_f32_e32 v34, 0xbfb8aa3b, v198
	v_fma_f32 v35, v198, s43, -v34
	v_rndne_f32_e32 v36, v34
	v_fmac_f32_e32 v35, 0xb2a5705f, v198
	v_sub_f32_e32 v34, v34, v36
	v_add_f32_e32 v34, v34, v35
	v_exp_f32_e32 v34, v34
	v_cvt_i32_f32_e32 v35, v36
	v_ldexp_f32 v34, v34, v35
	v_mul_f32_e32 v35, 0xbfb8aa3b, v199
	v_fma_f32 v36, v199, s43, -v35
	v_rndne_f32_e32 v37, v35
	v_fmac_f32_e32 v36, 0xb2a5705f, v199
	v_sub_f32_e32 v35, v35, v37
	v_add_f32_e32 v35, v35, v36
	v_exp_f32_e32 v35, v35
	v_cvt_i32_f32_e32 v36, v37
	v_cndmask_b32_e32 v34, 0, v34, vcc
	v_cmp_ngt_f32_e32 vcc, s35, v198
	v_ldexp_f32 v35, v35, v36
	s_nop 0
	v_cndmask_b32_e32 v34, v179, v34, vcc
	v_cmp_nlt_f32_e32 vcc, s34, v199
	s_nop 1
	v_cndmask_b32_e32 v35, 0, v35, vcc
	v_cmp_ngt_f32_e32 vcc, s35, v199
	s_nop 1
	v_cndmask_b32_e32 v35, v179, v35, vcc
	v_pk_add_f32 v[28:29], v[34:35], 1.0 op_sel_hi:[1,0]
	s_nop 0
	v_div_scale_f32 v34, s[2:3], v29, v29, v199
	v_rcp_f32_e32 v35, v34
	s_nop 0
	v_fma_f32 v36, -v34, v35, 1.0
	v_fmac_f32_e32 v35, v36, v35
	v_div_scale_f32 v36, vcc, v199, v29, v199
	v_mul_f32_e32 v37, v36, v35
	v_fma_f32 v38, -v34, v37, v36
	v_fmac_f32_e32 v37, v38, v35
	v_fma_f32 v34, -v34, v37, v36
	v_div_fmas_f32 v34, v34, v35, v37
	v_div_fixup_f32 v25, v34, v29, v199
	v_div_scale_f32 v29, s[2:3], v28, v28, v198
	v_rcp_f32_e32 v34, v29
	s_nop 0
	v_fma_f32 v35, -v29, v34, 1.0
	v_fmac_f32_e32 v34, v35, v34
	v_div_scale_f32 v35, vcc, v198, v28, v198
	v_mul_f32_e32 v36, v35, v34
	v_fma_f32 v37, -v29, v36, v35
	v_fmac_f32_e32 v36, v37, v34
	v_fma_f32 v29, -v29, v36, v35
	v_div_fmas_f32 v29, v29, v34, v36
	v_div_fixup_f32 v24, v29, v28, v198
	v_pk_mul_f32 v[4:5], v[4:5], v[24:25]
	v_cmp_nlt_f32_e32 vcc, s34, v200
	v_pk_fma_f32 v[24:25], v[4:5], v[4:5], v[32:33]
	v_mul_f32_e32 v28, v5, v5
	v_pk_add_f32 v[24:25], v[28:29], v[24:25] op_sel_hi:[0,1]
	v_mul_f32_e32 v28, 0xbfb8aa3b, v200
	v_fma_f32 v29, v200, s43, -v28
	v_rndne_f32_e32 v32, v28
	v_fmac_f32_e32 v29, 0xb2a5705f, v200
	v_sub_f32_e32 v28, v28, v32
	v_add_f32_e32 v28, v28, v29
	v_exp_f32_e32 v28, v28
	v_cvt_i32_f32_e32 v29, v32
	v_ldexp_f32 v28, v28, v29
	v_mul_f32_e32 v29, 0xbfb8aa3b, v201
	v_fma_f32 v32, v201, s43, -v29
	v_rndne_f32_e32 v33, v29
	v_fmac_f32_e32 v32, 0xb2a5705f, v201
	v_sub_f32_e32 v29, v29, v33
	v_add_f32_e32 v29, v29, v32
	v_exp_f32_e32 v29, v29
	v_cvt_i32_f32_e32 v32, v33
	v_cndmask_b32_e32 v28, 0, v28, vcc
	v_cmp_ngt_f32_e32 vcc, s35, v200
	v_ldexp_f32 v29, v29, v32
	s_nop 0
	v_cndmask_b32_e32 v28, v179, v28, vcc
	v_cmp_nlt_f32_e32 vcc, s34, v201
	s_nop 1
	v_cndmask_b32_e32 v29, 0, v29, vcc
	v_cmp_ngt_f32_e32 vcc, s35, v201
	s_nop 1
	v_cndmask_b32_e32 v29, v179, v29, vcc
	v_pk_add_f32 v[28:29], v[28:29], 1.0 op_sel_hi:[1,0]
	s_nop 0
	v_div_scale_f32 v30, s[2:3], v29, v29, v201
	v_rcp_f32_e32 v31, v30
	s_nop 0
	v_fma_f32 v32, -v30, v31, 1.0
	v_fmac_f32_e32 v31, v32, v31
	v_div_scale_f32 v32, vcc, v201, v29, v201
	v_mul_f32_e32 v33, v32, v31
	v_fma_f32 v34, -v30, v33, v32
	v_fmac_f32_e32 v33, v34, v31
	v_fma_f32 v30, -v30, v33, v32
	v_div_fmas_f32 v30, v30, v31, v33
	v_div_fixup_f32 v27, v30, v29, v201
	v_div_scale_f32 v29, s[2:3], v28, v28, v200
	v_rcp_f32_e32 v30, v29
	s_nop 0
	v_fma_f32 v31, -v29, v30, 1.0
	v_fmac_f32_e32 v30, v31, v30
	v_div_scale_f32 v31, vcc, v200, v28, v200
	v_mul_f32_e32 v32, v31, v30
	v_fma_f32 v33, -v29, v32, v31
	v_fmac_f32_e32 v32, v33, v30
	v_fma_f32 v29, -v29, v32, v31
	v_div_fmas_f32 v29, v29, v30, v32
	v_div_fixup_f32 v26, v29, v28, v200
	v_pk_mul_f32 v[6:7], v[6:7], v[26:27]
	v_cmp_nlt_f32_e32 vcc, s34, v206
	v_pk_fma_f32 v[24:25], v[6:7], v[6:7], v[24:25]
	v_mul_f32_e32 v26, v7, v7
	v_pk_add_f32 v[24:25], v[26:27], v[24:25] op_sel_hi:[0,1]
	v_mul_f32_e32 v26, 0xbfb8aa3b, v206
	v_fma_f32 v27, v206, s43, -v26
	v_rndne_f32_e32 v28, v26
	v_fmac_f32_e32 v27, 0xb2a5705f, v206
	v_sub_f32_e32 v26, v26, v28
	v_add_f32_e32 v26, v26, v27
	v_exp_f32_e32 v26, v26
	v_cvt_i32_f32_e32 v27, v28
	v_ldexp_f32 v26, v26, v27
	v_mul_f32_e32 v27, 0xbfb8aa3b, v207
	v_fma_f32 v28, v207, s43, -v27
	v_rndne_f32_e32 v29, v27
	v_fmac_f32_e32 v28, 0xb2a5705f, v207
	v_sub_f32_e32 v27, v27, v29
	v_add_f32_e32 v27, v27, v28
	v_exp_f32_e32 v27, v27
	v_cvt_i32_f32_e32 v28, v29
	v_cndmask_b32_e32 v26, 0, v26, vcc
	v_cmp_ngt_f32_e32 vcc, s35, v206
	v_ldexp_f32 v27, v27, v28
	s_nop 0
	v_cndmask_b32_e32 v26, v179, v26, vcc
	v_cmp_nlt_f32_e32 vcc, s34, v207
	s_nop 1
	v_cndmask_b32_e32 v27, 0, v27, vcc
	v_cmp_ngt_f32_e32 vcc, s35, v207
	s_nop 1
	v_cndmask_b32_e32 v27, v179, v27, vcc
	v_pk_add_f32 v[20:21], v[26:27], 1.0 op_sel_hi:[1,0]
	s_nop 0
	v_div_scale_f32 v26, s[2:3], v21, v21, v207
	v_rcp_f32_e32 v27, v26
	s_nop 0
	v_fma_f32 v28, -v26, v27, 1.0
	v_fmac_f32_e32 v27, v28, v27
	v_div_scale_f32 v28, vcc, v207, v21, v207
	v_mul_f32_e32 v29, v28, v27
	v_fma_f32 v30, -v26, v29, v28
	v_fmac_f32_e32 v29, v30, v27
	v_fma_f32 v26, -v26, v29, v28
	v_div_fmas_f32 v26, v26, v27, v29
	v_div_fixup_f32 v17, v26, v21, v207
	v_div_scale_f32 v21, s[2:3], v20, v20, v206
	v_rcp_f32_e32 v26, v21
	s_nop 0
	v_fma_f32 v27, -v21, v26, 1.0
	v_fmac_f32_e32 v26, v27, v26
	v_div_scale_f32 v27, vcc, v206, v20, v206
	v_mul_f32_e32 v28, v27, v26
	v_fma_f32 v29, -v21, v28, v27
	v_fmac_f32_e32 v28, v29, v26
	v_fma_f32 v21, -v21, v28, v27
	v_div_fmas_f32 v21, v21, v26, v28
	v_div_fixup_f32 v16, v21, v20, v206
	v_pk_mul_f32 v[8:9], v[8:9], v[16:17]
	v_cmp_nlt_f32_e32 vcc, s34, v208
	v_pk_fma_f32 v[16:17], v[8:9], v[8:9], v[24:25]
	v_mul_f32_e32 v20, v9, v9
	v_pk_add_f32 v[16:17], v[20:21], v[16:17] op_sel_hi:[0,1]
	v_mul_f32_e32 v20, 0xbfb8aa3b, v208
	v_fma_f32 v21, v208, s43, -v20
	v_rndne_f32_e32 v24, v20
	v_fmac_f32_e32 v21, 0xb2a5705f, v208
	v_sub_f32_e32 v20, v20, v24
	v_add_f32_e32 v20, v20, v21
	v_exp_f32_e32 v20, v20
	v_cvt_i32_f32_e32 v21, v24
	v_ldexp_f32 v20, v20, v21
	v_mul_f32_e32 v21, 0xbfb8aa3b, v209
	v_fma_f32 v24, v209, s43, -v21
	v_rndne_f32_e32 v25, v21
	v_fmac_f32_e32 v24, 0xb2a5705f, v209
	v_sub_f32_e32 v21, v21, v25
	v_add_f32_e32 v21, v21, v24
	v_exp_f32_e32 v21, v21
	v_cvt_i32_f32_e32 v24, v25
	v_cndmask_b32_e32 v20, 0, v20, vcc
	v_cmp_ngt_f32_e32 vcc, s35, v208
	v_ldexp_f32 v21, v21, v24
	s_nop 0
	v_cndmask_b32_e32 v20, v179, v20, vcc
	v_cmp_nlt_f32_e32 vcc, s34, v209
	s_nop 1
	v_cndmask_b32_e32 v21, 0, v21, vcc
	v_cmp_ngt_f32_e32 vcc, s35, v209
	s_nop 1
	v_cndmask_b32_e32 v21, v179, v21, vcc
	v_pk_add_f32 v[20:21], v[20:21], 1.0 op_sel_hi:[1,0]
	s_nop 0
	v_div_scale_f32 v22, s[2:3], v21, v21, v209
	v_rcp_f32_e32 v23, v22
	s_nop 0
	v_fma_f32 v24, -v22, v23, 1.0
	v_fmac_f32_e32 v23, v24, v23
	v_div_scale_f32 v24, vcc, v209, v21, v209
	v_mul_f32_e32 v25, v24, v23
	v_fma_f32 v26, -v22, v25, v24
	v_fmac_f32_e32 v25, v26, v23
	v_fma_f32 v22, -v22, v25, v24
	v_div_fmas_f32 v22, v22, v23, v25
	v_div_fixup_f32 v19, v22, v21, v209
	v_div_scale_f32 v21, s[2:3], v20, v20, v208
	v_rcp_f32_e32 v22, v21
	s_nop 0
	v_fma_f32 v23, -v21, v22, 1.0
	v_fmac_f32_e32 v22, v23, v22
	v_div_scale_f32 v23, vcc, v208, v20, v208
	v_mul_f32_e32 v24, v23, v22
	v_fma_f32 v25, -v21, v24, v23
	v_fmac_f32_e32 v24, v25, v22
	v_fma_f32 v21, -v21, v24, v23
	v_div_fmas_f32 v21, v21, v22, v24
	v_div_fixup_f32 v18, v21, v20, v208
	v_pk_mul_f32 v[10:11], v[10:11], v[18:19]
	s_waitcnt vmcnt(0)
	v_cmp_nlt_f32_e32 vcc, s34, v214
	v_pk_fma_f32 v[16:17], v[10:11], v[10:11], v[16:17]
	v_mul_f32_e32 v18, v11, v11
	v_pk_add_f32 v[16:17], v[18:19], v[16:17] op_sel_hi:[0,1]
	v_mul_f32_e32 v18, 0xbfb8aa3b, v214
	v_fma_f32 v19, v214, s43, -v18
	v_rndne_f32_e32 v20, v18
	v_fmac_f32_e32 v19, 0xb2a5705f, v214
	v_sub_f32_e32 v18, v18, v20
	v_add_f32_e32 v18, v18, v19
	v_exp_f32_e32 v18, v18
	v_cvt_i32_f32_e32 v19, v20
	v_ldexp_f32 v18, v18, v19
	v_mul_f32_e32 v19, 0xbfb8aa3b, v215
	v_fma_f32 v20, v215, s43, -v19
	v_rndne_f32_e32 v21, v19
	v_fmac_f32_e32 v20, 0xb2a5705f, v215
	v_sub_f32_e32 v19, v19, v21
	v_add_f32_e32 v19, v19, v20
	v_exp_f32_e32 v19, v19
	v_cvt_i32_f32_e32 v20, v21
	v_cndmask_b32_e32 v18, 0, v18, vcc
	v_cmp_ngt_f32_e32 vcc, s35, v214
	v_ldexp_f32 v19, v19, v20
	s_nop 0
	v_cndmask_b32_e32 v18, v179, v18, vcc
	v_cmp_nlt_f32_e32 vcc, s34, v215
	s_nop 1
	v_cndmask_b32_e32 v19, 0, v19, vcc
	v_cmp_ngt_f32_e32 vcc, s35, v215
	s_nop 1
	v_cndmask_b32_e32 v19, v179, v19, vcc
	v_pk_add_f32 v[18:19], v[18:19], 1.0 op_sel_hi:[1,0]
	s_nop 0
	v_div_scale_f32 v20, s[2:3], v19, v19, v215
	v_rcp_f32_e32 v21, v20
	s_nop 0
	v_fma_f32 v22, -v20, v21, 1.0
	v_fmac_f32_e32 v21, v22, v21
	v_div_scale_f32 v22, vcc, v215, v19, v215
	v_mul_f32_e32 v23, v22, v21
	v_fma_f32 v24, -v20, v23, v22
	v_fmac_f32_e32 v23, v24, v21
	v_fma_f32 v20, -v20, v23, v22
	v_div_fmas_f32 v20, v20, v21, v23
	v_div_fixup_f32 v19, v20, v19, v215
	v_div_scale_f32 v20, s[2:3], v18, v18, v214
	v_rcp_f32_e32 v21, v20
	s_nop 0
	v_fma_f32 v22, -v20, v21, 1.0
	v_fmac_f32_e32 v21, v22, v21
	v_div_scale_f32 v22, vcc, v214, v18, v214
	v_mul_f32_e32 v23, v22, v21
	v_fma_f32 v24, -v20, v23, v22
	v_fmac_f32_e32 v23, v24, v21
	v_fma_f32 v20, -v20, v23, v22
	v_div_fmas_f32 v20, v20, v21, v23
	v_div_fixup_f32 v18, v20, v18, v214
	v_pk_mul_f32 v[12:13], v[12:13], v[18:19]
	v_cmp_nlt_f32_e32 vcc, s34, v216
	v_pk_fma_f32 v[16:17], v[12:13], v[12:13], v[16:17]
	v_mul_f32_e32 v18, v13, v13
	v_pk_add_f32 v[16:17], v[18:19], v[16:17] op_sel_hi:[0,1]
	v_mul_f32_e32 v18, 0xbfb8aa3b, v216
	v_fma_f32 v19, v216, s43, -v18
	v_rndne_f32_e32 v20, v18
	v_fmac_f32_e32 v19, 0xb2a5705f, v216
	v_sub_f32_e32 v18, v18, v20
	v_add_f32_e32 v18, v18, v19
	v_exp_f32_e32 v18, v18
	v_cvt_i32_f32_e32 v19, v20
	v_ldexp_f32 v18, v18, v19
	v_mul_f32_e32 v19, 0xbfb8aa3b, v217
	v_fma_f32 v20, v217, s43, -v19
	v_rndne_f32_e32 v21, v19
	v_fmac_f32_e32 v20, 0xb2a5705f, v217
	v_sub_f32_e32 v19, v19, v21
	v_add_f32_e32 v19, v19, v20
	v_exp_f32_e32 v19, v19
	v_cvt_i32_f32_e32 v20, v21
	v_cndmask_b32_e32 v18, 0, v18, vcc
	v_cmp_ngt_f32_e32 vcc, s35, v216
	v_ldexp_f32 v19, v19, v20
	s_nop 0
	v_cndmask_b32_e32 v18, v179, v18, vcc
	v_cmp_nlt_f32_e32 vcc, s34, v217
	s_nop 1
	v_cndmask_b32_e32 v19, 0, v19, vcc
	v_cmp_ngt_f32_e32 vcc, s35, v217
	s_nop 1
	v_cndmask_b32_e32 v19, v179, v19, vcc
	v_pk_add_f32 v[18:19], v[18:19], 1.0 op_sel_hi:[1,0]
	s_nop 0
	v_div_scale_f32 v20, s[2:3], v19, v19, v217
	v_rcp_f32_e32 v21, v20
	s_nop 0
	v_fma_f32 v22, -v20, v21, 1.0
	v_fmac_f32_e32 v21, v22, v21
	v_div_scale_f32 v22, vcc, v217, v19, v217
	v_mul_f32_e32 v23, v22, v21
	v_fma_f32 v24, -v20, v23, v22
	v_fmac_f32_e32 v23, v24, v21
	v_fma_f32 v20, -v20, v23, v22
	v_div_fmas_f32 v20, v20, v21, v23
	v_div_fixup_f32 v19, v20, v19, v217
	v_div_scale_f32 v20, s[2:3], v18, v18, v216
	v_rcp_f32_e32 v21, v20
	s_nop 0
	v_fma_f32 v22, -v20, v21, 1.0
	v_fmac_f32_e32 v21, v22, v21
	v_div_scale_f32 v22, vcc, v216, v18, v216
	v_mul_f32_e32 v23, v22, v21
	v_fma_f32 v24, -v20, v23, v22
	v_fmac_f32_e32 v23, v24, v21
	v_fma_f32 v20, -v20, v23, v22
	v_div_fmas_f32 v20, v20, v21, v23
	v_div_fixup_f32 v18, v20, v18, v216
	v_pk_mul_f32 v[14:15], v[14:15], v[18:19]
	s_nop 0
	v_pk_fma_f32 v[16:17], v[14:15], v[14:15], v[16:17]
	v_mul_f32_e32 v18, v15, v15
	v_pk_add_f32 v[16:17], v[18:19], v[16:17] op_sel_hi:[0,1]
	v_mov_b32_e32 v17, v16
	s_nop 1
	v_permlane32_swap_b32_e32 v16, v17
	s_and_saveexec_b64 s[4:5], s[48:49]
	s_cbranch_execz .LBB0_1284
	v_add_f32_e32 v16, v16, v17
	ds_write_b32 v97, v16 offset:1024
	s_branch .LBB0_1284
